# scan operands double-buffered (one LDS wait per step) + S5 helper MFMA sections with batched LDS reads
# speedup vs baseline: 1.0395x; 1.0016x over previous
.LBB0_390:
	s_and_b32 s3, s2, 1
	s_mul_i32 s8, s3, 0x5000
	v_add_u32_e32 v2, s8, v136
	s_mul_i32 s8, s2, 0xab
	s_bfe_u32 s8, s8, 0x70009
	s_mul_i32 s8, s8, 3
	s_sub_i32 s8, s2, s8
	s_and_b32 s8, s8, 0xff
	s_mulk_i32 s8, 0x1100
	v_add_u32_e32 v3, s8, v137
	v_lshl_add_u32 v1, s3, 12, v137
	ds_read_b128 v[176:179], v2 offset:4096
	ds_read_b128 v[180:183], v2 offset:4112
	ds_read_b128 v[200:203], v2 offset:12288
	ds_read_b128 v[204:207], v2 offset:12304
	ds_read_b64 v[216:217], v3 offset:40960
	ds_read_b128 v[184:187], v2 offset:0
	ds_read_b128 v[188:191], v2 offset:16
	ds_read_b128 v[192:195], v2 offset:8192
	ds_read_b128 v[196:199], v2 offset:8208
	s_waitcnt lgkmcnt(0)
	v_pk_mul_f32 v[164:165], v[72:73], v[176:177]
	v_pk_mul_f32 v[166:167], v[80:81], v[176:177]
	ds_read_b128 v[208:211], v2 offset:16384
	v_pk_fma_f32 v[164:165], v[74:75], v[178:179], v[164:165]
	v_pk_fma_f32 v[166:167], v[82:83], v[178:179], v[166:167]
	ds_read_b128 v[212:215], v2 offset:16400
	v_pk_fma_f32 v[164:165], v[76:77], v[180:181], v[164:165]
	v_pk_fma_f32 v[166:167], v[84:85], v[180:181], v[166:167]
	ds_read_b128 v[4:7], v2 offset:4352
	v_pk_fma_f32 v[164:165], v[78:79], v[182:183], v[164:165]
	v_pk_fma_f32 v[166:167], v[86:87], v[182:183], v[166:167]
	ds_read_b128 v[8:11], v2 offset:4368
	v_pk_mul_f32 v[218:219], v[216:217], v[200:201] op_sel_hi:[0,1]
	v_pk_mul_f32 v[226:227], v[216:217], v[200:201] op_sel:[1,0]
	ds_read_b128 v[40:43], v2 offset:12544
	v_pk_mul_f32 v[220:221], v[216:217], v[202:203] op_sel_hi:[0,1]
	v_pk_mul_f32 v[228:229], v[216:217], v[202:203] op_sel:[1,0]
	ds_read_b128 v[44:47], v2 offset:12560
	v_pk_mul_f32 v[222:223], v[216:217], v[204:205] op_sel_hi:[0,1]
	v_pk_mul_f32 v[230:231], v[216:217], v[204:205] op_sel:[1,0]
	ds_read_b64 v[26:27], v3 offset:41216
	v_pk_mul_f32 v[224:225], v[216:217], v[206:207] op_sel_hi:[0,1]
	v_pk_mul_f32 v[234:235], v[216:217], v[206:207] op_sel:[1,0]
	ds_read_b128 v[12:15], v2 offset:256
	v_add_f32_e32 v172, v164, v165
	v_add_f32_e32 v174, v166, v167
	ds_read_b128 v[28:31], v2 offset:272
	v_pk_fma_f32 v[218:219], v[72:73], v[184:185], v[218:219]
	v_pk_fma_f32 v[226:227], v[80:81], v[184:185], v[226:227]
	ds_read_b128 v[32:35], v2 offset:8448
	v_pk_fma_f32 v[220:221], v[74:75], v[186:187], v[220:221]
	v_pk_fma_f32 v[228:229], v[82:83], v[186:187], v[228:229]
	ds_read_b128 v[36:39], v2 offset:8464
	v_add_f32_dpp v172, v172, v172 quad_perm:[1,0,3,2] row_mask:0xf bank_mask:0xf bound_ctrl:1
	v_add_f32_dpp v174, v174, v174 quad_perm:[1,0,3,2] row_mask:0xf bank_mask:0xf bound_ctrl:1
	v_pk_fma_f32 v[222:223], v[76:77], v[188:189], v[222:223]
	v_pk_fma_f32 v[230:231], v[84:85], v[188:189], v[230:231]
	v_pk_fma_f32 v[224:225], v[78:79], v[190:191], v[224:225]
	v_pk_fma_f32 v[234:235], v[86:87], v[190:191], v[234:235]
	v_add_f32_dpp v172, v172, v172 quad_perm:[2,3,0,1] row_mask:0xf bank_mask:0xf bound_ctrl:1
	v_add_f32_dpp v174, v174, v174 quad_perm:[2,3,0,1] row_mask:0xf bank_mask:0xf bound_ctrl:1
	s_nop 0
	v_add_f32_dpp v172, v172, v172 row_half_mirror row_mask:0xf bank_mask:0xf bound_ctrl:1
	v_add_f32_dpp v174, v174, v174 row_half_mirror row_mask:0xf bank_mask:0xf bound_ctrl:1
	v_pk_fma_f32 v[72:73], v[192:193], v[172:173], v[218:219] op_sel_hi:[1,0,1]
	v_pk_fma_f32 v[80:81], v[192:193], v[174:175], v[226:227] op_sel_hi:[1,0,1]
	v_pk_fma_f32 v[74:75], v[194:195], v[172:173], v[220:221] op_sel_hi:[1,0,1]
	v_pk_fma_f32 v[82:83], v[194:195], v[174:175], v[228:229] op_sel_hi:[1,0,1]
	v_pk_fma_f32 v[76:77], v[196:197], v[172:173], v[222:223] op_sel_hi:[1,0,1]
	v_pk_fma_f32 v[84:85], v[196:197], v[174:175], v[230:231] op_sel_hi:[1,0,1]
	v_pk_fma_f32 v[78:79], v[198:199], v[172:173], v[224:225] op_sel_hi:[1,0,1]
	v_pk_fma_f32 v[86:87], v[198:199], v[174:175], v[234:235] op_sel_hi:[1,0,1]
	s_waitcnt lgkmcnt(0)
	v_pk_mul_f32 v[164:165], v[72:73], v[4:5]
	v_pk_mul_f32 v[166:167], v[80:81], v[4:5]
	ds_read_b128 v[48:51], v2 offset:16640
	v_pk_mul_f32 v[168:169], v[72:73], v[208:209]
	v_pk_mul_f32 v[170:171], v[80:81], v[208:209]
	ds_read_b128 v[52:55], v2 offset:16656
	v_pk_fma_f32 v[164:165], v[74:75], v[6:7], v[164:165]
	v_pk_fma_f32 v[166:167], v[82:83], v[6:7], v[166:167]
	ds_read_b128 v[176:179], v2 offset:4608
	v_pk_fma_f32 v[168:169], v[74:75], v[210:211], v[168:169]
	v_pk_fma_f32 v[170:171], v[82:83], v[210:211], v[170:171]
	ds_read_b128 v[180:183], v2 offset:4624
	v_pk_fma_f32 v[164:165], v[76:77], v[8:9], v[164:165]
	v_pk_fma_f32 v[166:167], v[84:85], v[8:9], v[166:167]
	ds_read_b128 v[200:203], v2 offset:12800
	v_pk_fma_f32 v[168:169], v[76:77], v[212:213], v[168:169]
	v_pk_fma_f32 v[170:171], v[84:85], v[212:213], v[170:171]
	ds_read_b128 v[204:207], v2 offset:12816
	v_pk_fma_f32 v[164:165], v[78:79], v[10:11], v[164:165]
	v_pk_fma_f32 v[166:167], v[86:87], v[10:11], v[166:167]
	ds_read_b64 v[216:217], v3 offset:41472
	v_pk_fma_f32 v[168:169], v[78:79], v[214:215], v[168:169]
	v_pk_fma_f32 v[170:171], v[86:87], v[214:215], v[170:171]
	ds_read_b128 v[184:187], v2 offset:512
	v_pk_mul_f32 v[218:219], v[26:27], v[40:41] op_sel_hi:[0,1]
	v_pk_mul_f32 v[226:227], v[26:27], v[40:41] op_sel:[1,0]
	ds_read_b128 v[188:191], v2 offset:528
	v_pk_mul_f32 v[220:221], v[26:27], v[42:43] op_sel_hi:[0,1]
	v_pk_mul_f32 v[228:229], v[26:27], v[42:43] op_sel:[1,0]
	ds_read_b128 v[192:195], v2 offset:8704
	v_pk_mul_f32 v[222:223], v[26:27], v[44:45] op_sel_hi:[0,1]
	v_pk_mul_f32 v[230:231], v[26:27], v[44:45] op_sel:[1,0]
	ds_read_b128 v[196:199], v2 offset:8720
	v_pk_mul_f32 v[224:225], v[26:27], v[46:47] op_sel_hi:[0,1]
	v_pk_mul_f32 v[234:235], v[26:27], v[46:47] op_sel:[1,0]
	v_add_f32_e32 v172, v164, v165
	v_add_f32_e32 v174, v166, v167
	v_add_f32_e32 v160, v168, v169
	v_add_f32_e32 v161, v170, v171
	v_pk_fma_f32 v[218:219], v[72:73], v[12:13], v[218:219]
	v_pk_fma_f32 v[226:227], v[80:81], v[12:13], v[226:227]
	v_pk_fma_f32 v[220:221], v[74:75], v[14:15], v[220:221]
	v_pk_fma_f32 v[228:229], v[82:83], v[14:15], v[228:229]
	v_add_f32_dpp v172, v172, v172 quad_perm:[1,0,3,2] row_mask:0xf bank_mask:0xf bound_ctrl:1
	v_add_f32_dpp v174, v174, v174 quad_perm:[1,0,3,2] row_mask:0xf bank_mask:0xf bound_ctrl:1
	v_add_f32_dpp v160, v160, v160 quad_perm:[1,0,3,2] row_mask:0xf bank_mask:0xf bound_ctrl:1
	v_add_f32_dpp v161, v161, v161 quad_perm:[1,0,3,2] row_mask:0xf bank_mask:0xf bound_ctrl:1
	v_pk_fma_f32 v[222:223], v[76:77], v[28:29], v[222:223]
	v_pk_fma_f32 v[230:231], v[84:85], v[28:29], v[230:231]
	v_pk_fma_f32 v[224:225], v[78:79], v[30:31], v[224:225]
	v_pk_fma_f32 v[234:235], v[86:87], v[30:31], v[234:235]
	v_add_f32_dpp v172, v172, v172 quad_perm:[2,3,0,1] row_mask:0xf bank_mask:0xf bound_ctrl:1
	v_add_f32_dpp v174, v174, v174 quad_perm:[2,3,0,1] row_mask:0xf bank_mask:0xf bound_ctrl:1
	v_add_f32_dpp v160, v160, v160 quad_perm:[2,3,0,1] row_mask:0xf bank_mask:0xf bound_ctrl:1
	v_add_f32_dpp v161, v161, v161 quad_perm:[2,3,0,1] row_mask:0xf bank_mask:0xf bound_ctrl:1
	v_add_f32_dpp v172, v172, v172 row_half_mirror row_mask:0xf bank_mask:0xf bound_ctrl:1
	v_add_f32_dpp v174, v174, v174 row_half_mirror row_mask:0xf bank_mask:0xf bound_ctrl:1
	v_add_f32_dpp v160, v160, v160 row_half_mirror row_mask:0xf bank_mask:0xf bound_ctrl:1
	v_add_f32_dpp v161, v161, v161 row_half_mirror row_mask:0xf bank_mask:0xf bound_ctrl:1
	v_pk_fma_f32 v[72:73], v[32:33], v[172:173], v[218:219] op_sel_hi:[1,0,1]
	v_pk_fma_f32 v[80:81], v[32:33], v[174:175], v[226:227] op_sel_hi:[1,0,1]
	v_pk_fma_f32 v[74:75], v[34:35], v[172:173], v[220:221] op_sel_hi:[1,0,1]
	v_pk_fma_f32 v[82:83], v[34:35], v[174:175], v[228:229] op_sel_hi:[1,0,1]
	v_pk_fma_f32 v[76:77], v[36:37], v[172:173], v[222:223] op_sel_hi:[1,0,1]
	v_pk_fma_f32 v[84:85], v[36:37], v[174:175], v[230:231] op_sel_hi:[1,0,1]
	v_pk_fma_f32 v[78:79], v[38:39], v[172:173], v[224:225] op_sel_hi:[1,0,1]
	v_pk_fma_f32 v[86:87], v[38:39], v[174:175], v[234:235] op_sel_hi:[1,0,1]
	ds_write_b64 v1, v[160:161] offset:54016
	s_waitcnt lgkmcnt(1)
	v_pk_mul_f32 v[164:165], v[72:73], v[176:177]
	v_pk_mul_f32 v[166:167], v[80:81], v[176:177]
	ds_read_b128 v[208:211], v2 offset:16896
	v_pk_mul_f32 v[168:169], v[72:73], v[48:49]
	v_pk_mul_f32 v[170:171], v[80:81], v[48:49]
	ds_read_b128 v[212:215], v2 offset:16912
	v_pk_fma_f32 v[164:165], v[74:75], v[178:179], v[164:165]
	v_pk_fma_f32 v[166:167], v[82:83], v[178:179], v[166:167]
	ds_read_b128 v[4:7], v2 offset:4864
	v_pk_fma_f32 v[168:169], v[74:75], v[50:51], v[168:169]
	v_pk_fma_f32 v[170:171], v[82:83], v[50:51], v[170:171]
	ds_read_b128 v[8:11], v2 offset:4880
	v_pk_fma_f32 v[164:165], v[76:77], v[180:181], v[164:165]
	v_pk_fma_f32 v[166:167], v[84:85], v[180:181], v[166:167]
	ds_read_b128 v[40:43], v2 offset:13056
	v_pk_fma_f32 v[168:169], v[76:77], v[52:53], v[168:169]
	v_pk_fma_f32 v[170:171], v[84:85], v[52:53], v[170:171]
	ds_read_b128 v[44:47], v2 offset:13072
	v_pk_fma_f32 v[164:165], v[78:79], v[182:183], v[164:165]
	v_pk_fma_f32 v[166:167], v[86:87], v[182:183], v[166:167]
	ds_read_b64 v[26:27], v3 offset:41728
	v_pk_fma_f32 v[168:169], v[78:79], v[54:55], v[168:169]
	v_pk_fma_f32 v[170:171], v[86:87], v[54:55], v[170:171]
	ds_read_b128 v[12:15], v2 offset:768
	v_pk_mul_f32 v[218:219], v[216:217], v[200:201] op_sel_hi:[0,1]
	v_pk_mul_f32 v[226:227], v[216:217], v[200:201] op_sel:[1,0]
	ds_read_b128 v[28:31], v2 offset:784
	v_pk_mul_f32 v[220:221], v[216:217], v[202:203] op_sel_hi:[0,1]
	v_pk_mul_f32 v[228:229], v[216:217], v[202:203] op_sel:[1,0]
	ds_read_b128 v[32:35], v2 offset:8960
	v_pk_mul_f32 v[222:223], v[216:217], v[204:205] op_sel_hi:[0,1]
	v_pk_mul_f32 v[230:231], v[216:217], v[204:205] op_sel:[1,0]
	ds_read_b128 v[36:39], v2 offset:8976
	v_pk_mul_f32 v[224:225], v[216:217], v[206:207] op_sel_hi:[0,1]
	v_pk_mul_f32 v[234:235], v[216:217], v[206:207] op_sel:[1,0]
	v_add_f32_e32 v172, v164, v165
	v_add_f32_e32 v174, v166, v167
	v_add_f32_e32 v160, v168, v169
	v_add_f32_e32 v161, v170, v171
	v_pk_fma_f32 v[218:219], v[72:73], v[184:185], v[218:219]
	v_pk_fma_f32 v[226:227], v[80:81], v[184:185], v[226:227]
	v_pk_fma_f32 v[220:221], v[74:75], v[186:187], v[220:221]
	v_pk_fma_f32 v[228:229], v[82:83], v[186:187], v[228:229]
	v_add_f32_dpp v172, v172, v172 quad_perm:[1,0,3,2] row_mask:0xf bank_mask:0xf bound_ctrl:1
	v_add_f32_dpp v174, v174, v174 quad_perm:[1,0,3,2] row_mask:0xf bank_mask:0xf bound_ctrl:1
	v_add_f32_dpp v160, v160, v160 quad_perm:[1,0,3,2] row_mask:0xf bank_mask:0xf bound_ctrl:1
	v_add_f32_dpp v161, v161, v161 quad_perm:[1,0,3,2] row_mask:0xf bank_mask:0xf bound_ctrl:1
	v_pk_fma_f32 v[222:223], v[76:77], v[188:189], v[222:223]
	v_pk_fma_f32 v[230:231], v[84:85], v[188:189], v[230:231]
	v_pk_fma_f32 v[224:225], v[78:79], v[190:191], v[224:225]
	v_pk_fma_f32 v[234:235], v[86:87], v[190:191], v[234:235]
	v_add_f32_dpp v172, v172, v172 quad_perm:[2,3,0,1] row_mask:0xf bank_mask:0xf bound_ctrl:1
	v_add_f32_dpp v174, v174, v174 quad_perm:[2,3,0,1] row_mask:0xf bank_mask:0xf bound_ctrl:1
	v_add_f32_dpp v160, v160, v160 quad_perm:[2,3,0,1] row_mask:0xf bank_mask:0xf bound_ctrl:1
	v_add_f32_dpp v161, v161, v161 quad_perm:[2,3,0,1] row_mask:0xf bank_mask:0xf bound_ctrl:1
	v_add_f32_dpp v172, v172, v172 row_half_mirror row_mask:0xf bank_mask:0xf bound_ctrl:1
	v_add_f32_dpp v174, v174, v174 row_half_mirror row_mask:0xf bank_mask:0xf bound_ctrl:1
	v_add_f32_dpp v160, v160, v160 row_half_mirror row_mask:0xf bank_mask:0xf bound_ctrl:1
	v_add_f32_dpp v161, v161, v161 row_half_mirror row_mask:0xf bank_mask:0xf bound_ctrl:1
	v_pk_fma_f32 v[72:73], v[192:193], v[172:173], v[218:219] op_sel_hi:[1,0,1]
	v_pk_fma_f32 v[80:81], v[192:193], v[174:175], v[226:227] op_sel_hi:[1,0,1]
	v_pk_fma_f32 v[74:75], v[194:195], v[172:173], v[220:221] op_sel_hi:[1,0,1]
	v_pk_fma_f32 v[82:83], v[194:195], v[174:175], v[228:229] op_sel_hi:[1,0,1]
	v_pk_fma_f32 v[76:77], v[196:197], v[172:173], v[222:223] op_sel_hi:[1,0,1]
	v_pk_fma_f32 v[84:85], v[196:197], v[174:175], v[230:231] op_sel_hi:[1,0,1]
	v_pk_fma_f32 v[78:79], v[198:199], v[172:173], v[224:225] op_sel_hi:[1,0,1]
	v_pk_fma_f32 v[86:87], v[198:199], v[174:175], v[234:235] op_sel_hi:[1,0,1]
	ds_write_b64 v1, v[160:161] offset:54272
	s_waitcnt lgkmcnt(1)
	v_pk_mul_f32 v[164:165], v[72:73], v[4:5]
	v_pk_mul_f32 v[166:167], v[80:81], v[4:5]
	ds_read_b128 v[48:51], v2 offset:17152
	v_pk_mul_f32 v[168:169], v[72:73], v[208:209]
	v_pk_mul_f32 v[170:171], v[80:81], v[208:209]
	ds_read_b128 v[52:55], v2 offset:17168
	v_pk_fma_f32 v[164:165], v[74:75], v[6:7], v[164:165]
	v_pk_fma_f32 v[166:167], v[82:83], v[6:7], v[166:167]
	ds_read_b128 v[176:179], v2 offset:5120
	v_pk_fma_f32 v[168:169], v[74:75], v[210:211], v[168:169]
	v_pk_fma_f32 v[170:171], v[82:83], v[210:211], v[170:171]
	ds_read_b128 v[180:183], v2 offset:5136
	v_pk_fma_f32 v[164:165], v[76:77], v[8:9], v[164:165]
	v_pk_fma_f32 v[166:167], v[84:85], v[8:9], v[166:167]
	ds_read_b128 v[200:203], v2 offset:13312
	v_pk_fma_f32 v[168:169], v[76:77], v[212:213], v[168:169]
	v_pk_fma_f32 v[170:171], v[84:85], v[212:213], v[170:171]
	ds_read_b128 v[204:207], v2 offset:13328
	v_pk_fma_f32 v[164:165], v[78:79], v[10:11], v[164:165]
	v_pk_fma_f32 v[166:167], v[86:87], v[10:11], v[166:167]
	ds_read_b64 v[216:217], v3 offset:41984
	v_pk_fma_f32 v[168:169], v[78:79], v[214:215], v[168:169]
	v_pk_fma_f32 v[170:171], v[86:87], v[214:215], v[170:171]
	ds_read_b128 v[184:187], v2 offset:1024
	v_pk_mul_f32 v[218:219], v[26:27], v[40:41] op_sel_hi:[0,1]
	v_pk_mul_f32 v[226:227], v[26:27], v[40:41] op_sel:[1,0]
	ds_read_b128 v[188:191], v2 offset:1040
	v_pk_mul_f32 v[220:221], v[26:27], v[42:43] op_sel_hi:[0,1]
	v_pk_mul_f32 v[228:229], v[26:27], v[42:43] op_sel:[1,0]
	ds_read_b128 v[192:195], v2 offset:9216
	v_pk_mul_f32 v[222:223], v[26:27], v[44:45] op_sel_hi:[0,1]
	v_pk_mul_f32 v[230:231], v[26:27], v[44:45] op_sel:[1,0]
	ds_read_b128 v[196:199], v2 offset:9232
	v_pk_mul_f32 v[224:225], v[26:27], v[46:47] op_sel_hi:[0,1]
	v_pk_mul_f32 v[234:235], v[26:27], v[46:47] op_sel:[1,0]
	v_add_f32_e32 v172, v164, v165
	v_add_f32_e32 v174, v166, v167
	v_add_f32_e32 v160, v168, v169
	v_add_f32_e32 v161, v170, v171
	v_pk_fma_f32 v[218:219], v[72:73], v[12:13], v[218:219]
	v_pk_fma_f32 v[226:227], v[80:81], v[12:13], v[226:227]
	v_pk_fma_f32 v[220:221], v[74:75], v[14:15], v[220:221]
	v_pk_fma_f32 v[228:229], v[82:83], v[14:15], v[228:229]
	v_add_f32_dpp v172, v172, v172 quad_perm:[1,0,3,2] row_mask:0xf bank_mask:0xf bound_ctrl:1
	v_add_f32_dpp v174, v174, v174 quad_perm:[1,0,3,2] row_mask:0xf bank_mask:0xf bound_ctrl:1
	v_add_f32_dpp v160, v160, v160 quad_perm:[1,0,3,2] row_mask:0xf bank_mask:0xf bound_ctrl:1
	v_add_f32_dpp v161, v161, v161 quad_perm:[1,0,3,2] row_mask:0xf bank_mask:0xf bound_ctrl:1
	v_pk_fma_f32 v[222:223], v[76:77], v[28:29], v[222:223]
	v_pk_fma_f32 v[230:231], v[84:85], v[28:29], v[230:231]
	v_pk_fma_f32 v[224:225], v[78:79], v[30:31], v[224:225]
	v_pk_fma_f32 v[234:235], v[86:87], v[30:31], v[234:235]
	v_add_f32_dpp v172, v172, v172 quad_perm:[2,3,0,1] row_mask:0xf bank_mask:0xf bound_ctrl:1
	v_add_f32_dpp v174, v174, v174 quad_perm:[2,3,0,1] row_mask:0xf bank_mask:0xf bound_ctrl:1
	v_add_f32_dpp v160, v160, v160 quad_perm:[2,3,0,1] row_mask:0xf bank_mask:0xf bound_ctrl:1
	v_add_f32_dpp v161, v161, v161 quad_perm:[2,3,0,1] row_mask:0xf bank_mask:0xf bound_ctrl:1
	v_add_f32_dpp v172, v172, v172 row_half_mirror row_mask:0xf bank_mask:0xf bound_ctrl:1
	v_add_f32_dpp v174, v174, v174 row_half_mirror row_mask:0xf bank_mask:0xf bound_ctrl:1
	v_add_f32_dpp v160, v160, v160 row_half_mirror row_mask:0xf bank_mask:0xf bound_ctrl:1
	v_add_f32_dpp v161, v161, v161 row_half_mirror row_mask:0xf bank_mask:0xf bound_ctrl:1
	v_pk_fma_f32 v[72:73], v[32:33], v[172:173], v[218:219] op_sel_hi:[1,0,1]
	v_pk_fma_f32 v[80:81], v[32:33], v[174:175], v[226:227] op_sel_hi:[1,0,1]
	v_pk_fma_f32 v[74:75], v[34:35], v[172:173], v[220:221] op_sel_hi:[1,0,1]
	v_pk_fma_f32 v[82:83], v[34:35], v[174:175], v[228:229] op_sel_hi:[1,0,1]
	v_pk_fma_f32 v[76:77], v[36:37], v[172:173], v[222:223] op_sel_hi:[1,0,1]
	v_pk_fma_f32 v[84:85], v[36:37], v[174:175], v[230:231] op_sel_hi:[1,0,1]
	v_pk_fma_f32 v[78:79], v[38:39], v[172:173], v[224:225] op_sel_hi:[1,0,1]
	v_pk_fma_f32 v[86:87], v[38:39], v[174:175], v[234:235] op_sel_hi:[1,0,1]
	ds_write_b64 v1, v[160:161] offset:54528
	s_waitcnt lgkmcnt(1)
	v_pk_mul_f32 v[164:165], v[72:73], v[176:177]
	v_pk_mul_f32 v[166:167], v[80:81], v[176:177]
	ds_read_b128 v[208:211], v2 offset:17408
	v_pk_mul_f32 v[168:169], v[72:73], v[48:49]
	v_pk_mul_f32 v[170:171], v[80:81], v[48:49]
	ds_read_b128 v[212:215], v2 offset:17424
	v_pk_fma_f32 v[164:165], v[74:75], v[178:179], v[164:165]
	v_pk_fma_f32 v[166:167], v[82:83], v[178:179], v[166:167]
	ds_read_b128 v[4:7], v2 offset:5376
	v_pk_fma_f32 v[168:169], v[74:75], v[50:51], v[168:169]
	v_pk_fma_f32 v[170:171], v[82:83], v[50:51], v[170:171]
	ds_read_b128 v[8:11], v2 offset:5392
	v_pk_fma_f32 v[164:165], v[76:77], v[180:181], v[164:165]
	v_pk_fma_f32 v[166:167], v[84:85], v[180:181], v[166:167]
	ds_read_b128 v[40:43], v2 offset:13568
	v_pk_fma_f32 v[168:169], v[76:77], v[52:53], v[168:169]
	v_pk_fma_f32 v[170:171], v[84:85], v[52:53], v[170:171]
	ds_read_b128 v[44:47], v2 offset:13584
	v_pk_fma_f32 v[164:165], v[78:79], v[182:183], v[164:165]
	v_pk_fma_f32 v[166:167], v[86:87], v[182:183], v[166:167]
	ds_read_b64 v[26:27], v3 offset:42240
	v_pk_fma_f32 v[168:169], v[78:79], v[54:55], v[168:169]
	v_pk_fma_f32 v[170:171], v[86:87], v[54:55], v[170:171]
	ds_read_b128 v[12:15], v2 offset:1280
	v_pk_mul_f32 v[218:219], v[216:217], v[200:201] op_sel_hi:[0,1]
	v_pk_mul_f32 v[226:227], v[216:217], v[200:201] op_sel:[1,0]
	ds_read_b128 v[28:31], v2 offset:1296
	v_pk_mul_f32 v[220:221], v[216:217], v[202:203] op_sel_hi:[0,1]
	v_pk_mul_f32 v[228:229], v[216:217], v[202:203] op_sel:[1,0]
	ds_read_b128 v[32:35], v2 offset:9472
	v_pk_mul_f32 v[222:223], v[216:217], v[204:205] op_sel_hi:[0,1]
	v_pk_mul_f32 v[230:231], v[216:217], v[204:205] op_sel:[1,0]
	ds_read_b128 v[36:39], v2 offset:9488
	v_pk_mul_f32 v[224:225], v[216:217], v[206:207] op_sel_hi:[0,1]
	v_pk_mul_f32 v[234:235], v[216:217], v[206:207] op_sel:[1,0]
	v_add_f32_e32 v172, v164, v165
	v_add_f32_e32 v174, v166, v167
	v_add_f32_e32 v160, v168, v169
	v_add_f32_e32 v161, v170, v171
	v_pk_fma_f32 v[218:219], v[72:73], v[184:185], v[218:219]
	v_pk_fma_f32 v[226:227], v[80:81], v[184:185], v[226:227]
	v_pk_fma_f32 v[220:221], v[74:75], v[186:187], v[220:221]
	v_pk_fma_f32 v[228:229], v[82:83], v[186:187], v[228:229]
	v_add_f32_dpp v172, v172, v172 quad_perm:[1,0,3,2] row_mask:0xf bank_mask:0xf bound_ctrl:1
	v_add_f32_dpp v174, v174, v174 quad_perm:[1,0,3,2] row_mask:0xf bank_mask:0xf bound_ctrl:1
	v_add_f32_dpp v160, v160, v160 quad_perm:[1,0,3,2] row_mask:0xf bank_mask:0xf bound_ctrl:1
	v_add_f32_dpp v161, v161, v161 quad_perm:[1,0,3,2] row_mask:0xf bank_mask:0xf bound_ctrl:1
	v_pk_fma_f32 v[222:223], v[76:77], v[188:189], v[222:223]
	v_pk_fma_f32 v[230:231], v[84:85], v[188:189], v[230:231]
	v_pk_fma_f32 v[224:225], v[78:79], v[190:191], v[224:225]
	v_pk_fma_f32 v[234:235], v[86:87], v[190:191], v[234:235]
	v_add_f32_dpp v172, v172, v172 quad_perm:[2,3,0,1] row_mask:0xf bank_mask:0xf bound_ctrl:1
	v_add_f32_dpp v174, v174, v174 quad_perm:[2,3,0,1] row_mask:0xf bank_mask:0xf bound_ctrl:1
	v_add_f32_dpp v160, v160, v160 quad_perm:[2,3,0,1] row_mask:0xf bank_mask:0xf bound_ctrl:1
	v_add_f32_dpp v161, v161, v161 quad_perm:[2,3,0,1] row_mask:0xf bank_mask:0xf bound_ctrl:1
	v_add_f32_dpp v172, v172, v172 row_half_mirror row_mask:0xf bank_mask:0xf bound_ctrl:1
	v_add_f32_dpp v174, v174, v174 row_half_mirror row_mask:0xf bank_mask:0xf bound_ctrl:1
	v_add_f32_dpp v160, v160, v160 row_half_mirror row_mask:0xf bank_mask:0xf bound_ctrl:1
	v_add_f32_dpp v161, v161, v161 row_half_mirror row_mask:0xf bank_mask:0xf bound_ctrl:1
	v_pk_fma_f32 v[72:73], v[192:193], v[172:173], v[218:219] op_sel_hi:[1,0,1]
	v_pk_fma_f32 v[80:81], v[192:193], v[174:175], v[226:227] op_sel_hi:[1,0,1]
	v_pk_fma_f32 v[74:75], v[194:195], v[172:173], v[220:221] op_sel_hi:[1,0,1]
	v_pk_fma_f32 v[82:83], v[194:195], v[174:175], v[228:229] op_sel_hi:[1,0,1]
	v_pk_fma_f32 v[76:77], v[196:197], v[172:173], v[222:223] op_sel_hi:[1,0,1]
	v_pk_fma_f32 v[84:85], v[196:197], v[174:175], v[230:231] op_sel_hi:[1,0,1]
	v_pk_fma_f32 v[78:79], v[198:199], v[172:173], v[224:225] op_sel_hi:[1,0,1]
	v_pk_fma_f32 v[86:87], v[198:199], v[174:175], v[234:235] op_sel_hi:[1,0,1]
	ds_write_b64 v1, v[160:161] offset:54784
	s_waitcnt lgkmcnt(1)
	v_pk_mul_f32 v[164:165], v[72:73], v[4:5]
	v_pk_mul_f32 v[166:167], v[80:81], v[4:5]
	ds_read_b128 v[48:51], v2 offset:17664
	v_pk_mul_f32 v[168:169], v[72:73], v[208:209]
	v_pk_mul_f32 v[170:171], v[80:81], v[208:209]
	ds_read_b128 v[52:55], v2 offset:17680
	v_pk_fma_f32 v[164:165], v[74:75], v[6:7], v[164:165]
	v_pk_fma_f32 v[166:167], v[82:83], v[6:7], v[166:167]
	ds_read_b128 v[176:179], v2 offset:5632
	v_pk_fma_f32 v[168:169], v[74:75], v[210:211], v[168:169]
	v_pk_fma_f32 v[170:171], v[82:83], v[210:211], v[170:171]
	ds_read_b128 v[180:183], v2 offset:5648
	v_pk_fma_f32 v[164:165], v[76:77], v[8:9], v[164:165]
	v_pk_fma_f32 v[166:167], v[84:85], v[8:9], v[166:167]
	ds_read_b128 v[200:203], v2 offset:13824
	v_pk_fma_f32 v[168:169], v[76:77], v[212:213], v[168:169]
	v_pk_fma_f32 v[170:171], v[84:85], v[212:213], v[170:171]
	ds_read_b128 v[204:207], v2 offset:13840
	v_pk_fma_f32 v[164:165], v[78:79], v[10:11], v[164:165]
	v_pk_fma_f32 v[166:167], v[86:87], v[10:11], v[166:167]
	ds_read_b64 v[216:217], v3 offset:42496
	v_pk_fma_f32 v[168:169], v[78:79], v[214:215], v[168:169]
	v_pk_fma_f32 v[170:171], v[86:87], v[214:215], v[170:171]
	ds_read_b128 v[184:187], v2 offset:1536
	v_pk_mul_f32 v[218:219], v[26:27], v[40:41] op_sel_hi:[0,1]
	v_pk_mul_f32 v[226:227], v[26:27], v[40:41] op_sel:[1,0]
	ds_read_b128 v[188:191], v2 offset:1552
	v_pk_mul_f32 v[220:221], v[26:27], v[42:43] op_sel_hi:[0,1]
	v_pk_mul_f32 v[228:229], v[26:27], v[42:43] op_sel:[1,0]
	ds_read_b128 v[192:195], v2 offset:9728
	v_pk_mul_f32 v[222:223], v[26:27], v[44:45] op_sel_hi:[0,1]
	v_pk_mul_f32 v[230:231], v[26:27], v[44:45] op_sel:[1,0]
	ds_read_b128 v[196:199], v2 offset:9744
	v_pk_mul_f32 v[224:225], v[26:27], v[46:47] op_sel_hi:[0,1]
	v_pk_mul_f32 v[234:235], v[26:27], v[46:47] op_sel:[1,0]
	v_add_f32_e32 v172, v164, v165
	v_add_f32_e32 v174, v166, v167
	v_add_f32_e32 v160, v168, v169
	v_add_f32_e32 v161, v170, v171
	v_pk_fma_f32 v[218:219], v[72:73], v[12:13], v[218:219]
	v_pk_fma_f32 v[226:227], v[80:81], v[12:13], v[226:227]
	v_pk_fma_f32 v[220:221], v[74:75], v[14:15], v[220:221]
	v_pk_fma_f32 v[228:229], v[82:83], v[14:15], v[228:229]
	v_add_f32_dpp v172, v172, v172 quad_perm:[1,0,3,2] row_mask:0xf bank_mask:0xf bound_ctrl:1
	v_add_f32_dpp v174, v174, v174 quad_perm:[1,0,3,2] row_mask:0xf bank_mask:0xf bound_ctrl:1
	v_add_f32_dpp v160, v160, v160 quad_perm:[1,0,3,2] row_mask:0xf bank_mask:0xf bound_ctrl:1
	v_add_f32_dpp v161, v161, v161 quad_perm:[1,0,3,2] row_mask:0xf bank_mask:0xf bound_ctrl:1
	v_pk_fma_f32 v[222:223], v[76:77], v[28:29], v[222:223]
	v_pk_fma_f32 v[230:231], v[84:85], v[28:29], v[230:231]
	v_pk_fma_f32 v[224:225], v[78:79], v[30:31], v[224:225]
	v_pk_fma_f32 v[234:235], v[86:87], v[30:31], v[234:235]
	v_add_f32_dpp v172, v172, v172 quad_perm:[2,3,0,1] row_mask:0xf bank_mask:0xf bound_ctrl:1
	v_add_f32_dpp v174, v174, v174 quad_perm:[2,3,0,1] row_mask:0xf bank_mask:0xf bound_ctrl:1
	v_add_f32_dpp v160, v160, v160 quad_perm:[2,3,0,1] row_mask:0xf bank_mask:0xf bound_ctrl:1
	v_add_f32_dpp v161, v161, v161 quad_perm:[2,3,0,1] row_mask:0xf bank_mask:0xf bound_ctrl:1
	v_add_f32_dpp v172, v172, v172 row_half_mirror row_mask:0xf bank_mask:0xf bound_ctrl:1
	v_add_f32_dpp v174, v174, v174 row_half_mirror row_mask:0xf bank_mask:0xf bound_ctrl:1
	v_add_f32_dpp v160, v160, v160 row_half_mirror row_mask:0xf bank_mask:0xf bound_ctrl:1
	v_add_f32_dpp v161, v161, v161 row_half_mirror row_mask:0xf bank_mask:0xf bound_ctrl:1
	v_pk_fma_f32 v[72:73], v[32:33], v[172:173], v[218:219] op_sel_hi:[1,0,1]
	v_pk_fma_f32 v[80:81], v[32:33], v[174:175], v[226:227] op_sel_hi:[1,0,1]
	v_pk_fma_f32 v[74:75], v[34:35], v[172:173], v[220:221] op_sel_hi:[1,0,1]
	v_pk_fma_f32 v[82:83], v[34:35], v[174:175], v[228:229] op_sel_hi:[1,0,1]
	v_pk_fma_f32 v[76:77], v[36:37], v[172:173], v[222:223] op_sel_hi:[1,0,1]
	v_pk_fma_f32 v[84:85], v[36:37], v[174:175], v[230:231] op_sel_hi:[1,0,1]
	v_pk_fma_f32 v[78:79], v[38:39], v[172:173], v[224:225] op_sel_hi:[1,0,1]
	v_pk_fma_f32 v[86:87], v[38:39], v[174:175], v[234:235] op_sel_hi:[1,0,1]
	ds_write_b64 v1, v[160:161] offset:55040
	s_waitcnt lgkmcnt(1)
	v_pk_mul_f32 v[164:165], v[72:73], v[176:177]
	v_pk_mul_f32 v[166:167], v[80:81], v[176:177]
	ds_read_b128 v[208:211], v2 offset:17920
	v_pk_mul_f32 v[168:169], v[72:73], v[48:49]
	v_pk_mul_f32 v[170:171], v[80:81], v[48:49]
	ds_read_b128 v[212:215], v2 offset:17936
	v_pk_fma_f32 v[164:165], v[74:75], v[178:179], v[164:165]
	v_pk_fma_f32 v[166:167], v[82:83], v[178:179], v[166:167]
	ds_read_b128 v[4:7], v2 offset:5888
	v_pk_fma_f32 v[168:169], v[74:75], v[50:51], v[168:169]
	v_pk_fma_f32 v[170:171], v[82:83], v[50:51], v[170:171]
	ds_read_b128 v[8:11], v2 offset:5904
	v_pk_fma_f32 v[164:165], v[76:77], v[180:181], v[164:165]
	v_pk_fma_f32 v[166:167], v[84:85], v[180:181], v[166:167]
	ds_read_b128 v[40:43], v2 offset:14080
	v_pk_fma_f32 v[168:169], v[76:77], v[52:53], v[168:169]
	v_pk_fma_f32 v[170:171], v[84:85], v[52:53], v[170:171]
	ds_read_b128 v[44:47], v2 offset:14096
	v_pk_fma_f32 v[164:165], v[78:79], v[182:183], v[164:165]
	v_pk_fma_f32 v[166:167], v[86:87], v[182:183], v[166:167]
	ds_read_b64 v[26:27], v3 offset:42752
	v_pk_fma_f32 v[168:169], v[78:79], v[54:55], v[168:169]
	v_pk_fma_f32 v[170:171], v[86:87], v[54:55], v[170:171]
	ds_read_b128 v[12:15], v2 offset:1792
	v_pk_mul_f32 v[218:219], v[216:217], v[200:201] op_sel_hi:[0,1]
	v_pk_mul_f32 v[226:227], v[216:217], v[200:201] op_sel:[1,0]
	ds_read_b128 v[28:31], v2 offset:1808
	v_pk_mul_f32 v[220:221], v[216:217], v[202:203] op_sel_hi:[0,1]
	v_pk_mul_f32 v[228:229], v[216:217], v[202:203] op_sel:[1,0]
	ds_read_b128 v[32:35], v2 offset:9984
	v_pk_mul_f32 v[222:223], v[216:217], v[204:205] op_sel_hi:[0,1]
	v_pk_mul_f32 v[230:231], v[216:217], v[204:205] op_sel:[1,0]
	ds_read_b128 v[36:39], v2 offset:10000
	v_pk_mul_f32 v[224:225], v[216:217], v[206:207] op_sel_hi:[0,1]
	v_pk_mul_f32 v[234:235], v[216:217], v[206:207] op_sel:[1,0]
	v_add_f32_e32 v172, v164, v165
	v_add_f32_e32 v174, v166, v167
	v_add_f32_e32 v160, v168, v169
	v_add_f32_e32 v161, v170, v171
	v_pk_fma_f32 v[218:219], v[72:73], v[184:185], v[218:219]
	v_pk_fma_f32 v[226:227], v[80:81], v[184:185], v[226:227]
	v_pk_fma_f32 v[220:221], v[74:75], v[186:187], v[220:221]
	v_pk_fma_f32 v[228:229], v[82:83], v[186:187], v[228:229]
	v_add_f32_dpp v172, v172, v172 quad_perm:[1,0,3,2] row_mask:0xf bank_mask:0xf bound_ctrl:1
	v_add_f32_dpp v174, v174, v174 quad_perm:[1,0,3,2] row_mask:0xf bank_mask:0xf bound_ctrl:1
	v_add_f32_dpp v160, v160, v160 quad_perm:[1,0,3,2] row_mask:0xf bank_mask:0xf bound_ctrl:1
	v_add_f32_dpp v161, v161, v161 quad_perm:[1,0,3,2] row_mask:0xf bank_mask:0xf bound_ctrl:1
	v_pk_fma_f32 v[222:223], v[76:77], v[188:189], v[222:223]
	v_pk_fma_f32 v[230:231], v[84:85], v[188:189], v[230:231]
	v_pk_fma_f32 v[224:225], v[78:79], v[190:191], v[224:225]
	v_pk_fma_f32 v[234:235], v[86:87], v[190:191], v[234:235]
	v_add_f32_dpp v172, v172, v172 quad_perm:[2,3,0,1] row_mask:0xf bank_mask:0xf bound_ctrl:1
	v_add_f32_dpp v174, v174, v174 quad_perm:[2,3,0,1] row_mask:0xf bank_mask:0xf bound_ctrl:1
	v_add_f32_dpp v160, v160, v160 quad_perm:[2,3,0,1] row_mask:0xf bank_mask:0xf bound_ctrl:1
	v_add_f32_dpp v161, v161, v161 quad_perm:[2,3,0,1] row_mask:0xf bank_mask:0xf bound_ctrl:1
	v_add_f32_dpp v172, v172, v172 row_half_mirror row_mask:0xf bank_mask:0xf bound_ctrl:1
	v_add_f32_dpp v174, v174, v174 row_half_mirror row_mask:0xf bank_mask:0xf bound_ctrl:1
	v_add_f32_dpp v160, v160, v160 row_half_mirror row_mask:0xf bank_mask:0xf bound_ctrl:1
	v_add_f32_dpp v161, v161, v161 row_half_mirror row_mask:0xf bank_mask:0xf bound_ctrl:1
	v_pk_fma_f32 v[72:73], v[192:193], v[172:173], v[218:219] op_sel_hi:[1,0,1]
	v_pk_fma_f32 v[80:81], v[192:193], v[174:175], v[226:227] op_sel_hi:[1,0,1]
	v_pk_fma_f32 v[74:75], v[194:195], v[172:173], v[220:221] op_sel_hi:[1,0,1]
	v_pk_fma_f32 v[82:83], v[194:195], v[174:175], v[228:229] op_sel_hi:[1,0,1]
	v_pk_fma_f32 v[76:77], v[196:197], v[172:173], v[222:223] op_sel_hi:[1,0,1]
	v_pk_fma_f32 v[84:85], v[196:197], v[174:175], v[230:231] op_sel_hi:[1,0,1]
	v_pk_fma_f32 v[78:79], v[198:199], v[172:173], v[224:225] op_sel_hi:[1,0,1]
	v_pk_fma_f32 v[86:87], v[198:199], v[174:175], v[234:235] op_sel_hi:[1,0,1]
	ds_write_b64 v1, v[160:161] offset:55296
	s_waitcnt lgkmcnt(1)
	v_pk_mul_f32 v[164:165], v[72:73], v[4:5]
	v_pk_mul_f32 v[166:167], v[80:81], v[4:5]
	ds_read_b128 v[48:51], v2 offset:18176
	v_pk_mul_f32 v[168:169], v[72:73], v[208:209]
	v_pk_mul_f32 v[170:171], v[80:81], v[208:209]
	ds_read_b128 v[52:55], v2 offset:18192
	v_pk_fma_f32 v[164:165], v[74:75], v[6:7], v[164:165]
	v_pk_fma_f32 v[166:167], v[82:83], v[6:7], v[166:167]
	ds_read_b128 v[176:179], v2 offset:6144
	v_pk_fma_f32 v[168:169], v[74:75], v[210:211], v[168:169]
	v_pk_fma_f32 v[170:171], v[82:83], v[210:211], v[170:171]
	ds_read_b128 v[180:183], v2 offset:6160
	v_pk_fma_f32 v[164:165], v[76:77], v[8:9], v[164:165]
	v_pk_fma_f32 v[166:167], v[84:85], v[8:9], v[166:167]
	ds_read_b128 v[200:203], v2 offset:14336
	v_pk_fma_f32 v[168:169], v[76:77], v[212:213], v[168:169]
	v_pk_fma_f32 v[170:171], v[84:85], v[212:213], v[170:171]
	ds_read_b128 v[204:207], v2 offset:14352
	v_pk_fma_f32 v[164:165], v[78:79], v[10:11], v[164:165]
	v_pk_fma_f32 v[166:167], v[86:87], v[10:11], v[166:167]
	ds_read_b64 v[216:217], v3 offset:43008
	v_pk_fma_f32 v[168:169], v[78:79], v[214:215], v[168:169]
	v_pk_fma_f32 v[170:171], v[86:87], v[214:215], v[170:171]
	ds_read_b128 v[184:187], v2 offset:2048
	v_pk_mul_f32 v[218:219], v[26:27], v[40:41] op_sel_hi:[0,1]
	v_pk_mul_f32 v[226:227], v[26:27], v[40:41] op_sel:[1,0]
	ds_read_b128 v[188:191], v2 offset:2064
	v_pk_mul_f32 v[220:221], v[26:27], v[42:43] op_sel_hi:[0,1]
	v_pk_mul_f32 v[228:229], v[26:27], v[42:43] op_sel:[1,0]
	ds_read_b128 v[192:195], v2 offset:10240
	v_pk_mul_f32 v[222:223], v[26:27], v[44:45] op_sel_hi:[0,1]
	v_pk_mul_f32 v[230:231], v[26:27], v[44:45] op_sel:[1,0]
	ds_read_b128 v[196:199], v2 offset:10256
	v_pk_mul_f32 v[224:225], v[26:27], v[46:47] op_sel_hi:[0,1]
	v_pk_mul_f32 v[234:235], v[26:27], v[46:47] op_sel:[1,0]
	v_add_f32_e32 v172, v164, v165
	v_add_f32_e32 v174, v166, v167
	v_add_f32_e32 v160, v168, v169
	v_add_f32_e32 v161, v170, v171
	v_pk_fma_f32 v[218:219], v[72:73], v[12:13], v[218:219]
	v_pk_fma_f32 v[226:227], v[80:81], v[12:13], v[226:227]
	v_pk_fma_f32 v[220:221], v[74:75], v[14:15], v[220:221]
	v_pk_fma_f32 v[228:229], v[82:83], v[14:15], v[228:229]
	v_add_f32_dpp v172, v172, v172 quad_perm:[1,0,3,2] row_mask:0xf bank_mask:0xf bound_ctrl:1
	v_add_f32_dpp v174, v174, v174 quad_perm:[1,0,3,2] row_mask:0xf bank_mask:0xf bound_ctrl:1
	v_add_f32_dpp v160, v160, v160 quad_perm:[1,0,3,2] row_mask:0xf bank_mask:0xf bound_ctrl:1
	v_add_f32_dpp v161, v161, v161 quad_perm:[1,0,3,2] row_mask:0xf bank_mask:0xf bound_ctrl:1
	v_pk_fma_f32 v[222:223], v[76:77], v[28:29], v[222:223]
	v_pk_fma_f32 v[230:231], v[84:85], v[28:29], v[230:231]
	v_pk_fma_f32 v[224:225], v[78:79], v[30:31], v[224:225]
	v_pk_fma_f32 v[234:235], v[86:87], v[30:31], v[234:235]
	v_add_f32_dpp v172, v172, v172 quad_perm:[2,3,0,1] row_mask:0xf bank_mask:0xf bound_ctrl:1
	v_add_f32_dpp v174, v174, v174 quad_perm:[2,3,0,1] row_mask:0xf bank_mask:0xf bound_ctrl:1
	v_add_f32_dpp v160, v160, v160 quad_perm:[2,3,0,1] row_mask:0xf bank_mask:0xf bound_ctrl:1
	v_add_f32_dpp v161, v161, v161 quad_perm:[2,3,0,1] row_mask:0xf bank_mask:0xf bound_ctrl:1
	v_add_f32_dpp v172, v172, v172 row_half_mirror row_mask:0xf bank_mask:0xf bound_ctrl:1
	v_add_f32_dpp v174, v174, v174 row_half_mirror row_mask:0xf bank_mask:0xf bound_ctrl:1
	v_add_f32_dpp v160, v160, v160 row_half_mirror row_mask:0xf bank_mask:0xf bound_ctrl:1
	v_add_f32_dpp v161, v161, v161 row_half_mirror row_mask:0xf bank_mask:0xf bound_ctrl:1
	v_pk_fma_f32 v[72:73], v[32:33], v[172:173], v[218:219] op_sel_hi:[1,0,1]
	v_pk_fma_f32 v[80:81], v[32:33], v[174:175], v[226:227] op_sel_hi:[1,0,1]
	v_pk_fma_f32 v[74:75], v[34:35], v[172:173], v[220:221] op_sel_hi:[1,0,1]
	v_pk_fma_f32 v[82:83], v[34:35], v[174:175], v[228:229] op_sel_hi:[1,0,1]
	v_pk_fma_f32 v[76:77], v[36:37], v[172:173], v[222:223] op_sel_hi:[1,0,1]
	v_pk_fma_f32 v[84:85], v[36:37], v[174:175], v[230:231] op_sel_hi:[1,0,1]
	v_pk_fma_f32 v[78:79], v[38:39], v[172:173], v[224:225] op_sel_hi:[1,0,1]
	v_pk_fma_f32 v[86:87], v[38:39], v[174:175], v[234:235] op_sel_hi:[1,0,1]
	ds_write_b64 v1, v[160:161] offset:55552
	s_waitcnt lgkmcnt(1)
	v_pk_mul_f32 v[164:165], v[72:73], v[176:177]
	v_pk_mul_f32 v[166:167], v[80:81], v[176:177]
	ds_read_b128 v[208:211], v2 offset:18432
	v_pk_mul_f32 v[168:169], v[72:73], v[48:49]
	v_pk_mul_f32 v[170:171], v[80:81], v[48:49]
	ds_read_b128 v[212:215], v2 offset:18448
	v_pk_fma_f32 v[164:165], v[74:75], v[178:179], v[164:165]
	v_pk_fma_f32 v[166:167], v[82:83], v[178:179], v[166:167]
	ds_read_b128 v[4:7], v2 offset:6400
	v_pk_fma_f32 v[168:169], v[74:75], v[50:51], v[168:169]
	v_pk_fma_f32 v[170:171], v[82:83], v[50:51], v[170:171]
	ds_read_b128 v[8:11], v2 offset:6416
	v_pk_fma_f32 v[164:165], v[76:77], v[180:181], v[164:165]
	v_pk_fma_f32 v[166:167], v[84:85], v[180:181], v[166:167]
	ds_read_b128 v[40:43], v2 offset:14592
	v_pk_fma_f32 v[168:169], v[76:77], v[52:53], v[168:169]
	v_pk_fma_f32 v[170:171], v[84:85], v[52:53], v[170:171]
	ds_read_b128 v[44:47], v2 offset:14608
	v_pk_fma_f32 v[164:165], v[78:79], v[182:183], v[164:165]
	v_pk_fma_f32 v[166:167], v[86:87], v[182:183], v[166:167]
	ds_read_b64 v[26:27], v3 offset:43264
	v_pk_fma_f32 v[168:169], v[78:79], v[54:55], v[168:169]
	v_pk_fma_f32 v[170:171], v[86:87], v[54:55], v[170:171]
	ds_read_b128 v[12:15], v2 offset:2304
	v_pk_mul_f32 v[218:219], v[216:217], v[200:201] op_sel_hi:[0,1]
	v_pk_mul_f32 v[226:227], v[216:217], v[200:201] op_sel:[1,0]
	ds_read_b128 v[28:31], v2 offset:2320
	v_pk_mul_f32 v[220:221], v[216:217], v[202:203] op_sel_hi:[0,1]
	v_pk_mul_f32 v[228:229], v[216:217], v[202:203] op_sel:[1,0]
	ds_read_b128 v[32:35], v2 offset:10496
	v_pk_mul_f32 v[222:223], v[216:217], v[204:205] op_sel_hi:[0,1]
	v_pk_mul_f32 v[230:231], v[216:217], v[204:205] op_sel:[1,0]
	ds_read_b128 v[36:39], v2 offset:10512
	v_pk_mul_f32 v[224:225], v[216:217], v[206:207] op_sel_hi:[0,1]
	v_pk_mul_f32 v[234:235], v[216:217], v[206:207] op_sel:[1,0]
	v_add_f32_e32 v172, v164, v165
	v_add_f32_e32 v174, v166, v167
	v_add_f32_e32 v160, v168, v169
	v_add_f32_e32 v161, v170, v171
	v_pk_fma_f32 v[218:219], v[72:73], v[184:185], v[218:219]
	v_pk_fma_f32 v[226:227], v[80:81], v[184:185], v[226:227]
	v_pk_fma_f32 v[220:221], v[74:75], v[186:187], v[220:221]
	v_pk_fma_f32 v[228:229], v[82:83], v[186:187], v[228:229]
	v_add_f32_dpp v172, v172, v172 quad_perm:[1,0,3,2] row_mask:0xf bank_mask:0xf bound_ctrl:1
	v_add_f32_dpp v174, v174, v174 quad_perm:[1,0,3,2] row_mask:0xf bank_mask:0xf bound_ctrl:1
	v_add_f32_dpp v160, v160, v160 quad_perm:[1,0,3,2] row_mask:0xf bank_mask:0xf bound_ctrl:1
	v_add_f32_dpp v161, v161, v161 quad_perm:[1,0,3,2] row_mask:0xf bank_mask:0xf bound_ctrl:1
	v_pk_fma_f32 v[222:223], v[76:77], v[188:189], v[222:223]
	v_pk_fma_f32 v[230:231], v[84:85], v[188:189], v[230:231]
	v_pk_fma_f32 v[224:225], v[78:79], v[190:191], v[224:225]
	v_pk_fma_f32 v[234:235], v[86:87], v[190:191], v[234:235]
	v_add_f32_dpp v172, v172, v172 quad_perm:[2,3,0,1] row_mask:0xf bank_mask:0xf bound_ctrl:1
	v_add_f32_dpp v174, v174, v174 quad_perm:[2,3,0,1] row_mask:0xf bank_mask:0xf bound_ctrl:1
	v_add_f32_dpp v160, v160, v160 quad_perm:[2,3,0,1] row_mask:0xf bank_mask:0xf bound_ctrl:1
	v_add_f32_dpp v161, v161, v161 quad_perm:[2,3,0,1] row_mask:0xf bank_mask:0xf bound_ctrl:1
	v_add_f32_dpp v172, v172, v172 row_half_mirror row_mask:0xf bank_mask:0xf bound_ctrl:1
	v_add_f32_dpp v174, v174, v174 row_half_mirror row_mask:0xf bank_mask:0xf bound_ctrl:1
	v_add_f32_dpp v160, v160, v160 row_half_mirror row_mask:0xf bank_mask:0xf bound_ctrl:1
	v_add_f32_dpp v161, v161, v161 row_half_mirror row_mask:0xf bank_mask:0xf bound_ctrl:1
	v_pk_fma_f32 v[72:73], v[192:193], v[172:173], v[218:219] op_sel_hi:[1,0,1]
	v_pk_fma_f32 v[80:81], v[192:193], v[174:175], v[226:227] op_sel_hi:[1,0,1]
	v_pk_fma_f32 v[74:75], v[194:195], v[172:173], v[220:221] op_sel_hi:[1,0,1]
	v_pk_fma_f32 v[82:83], v[194:195], v[174:175], v[228:229] op_sel_hi:[1,0,1]
	v_pk_fma_f32 v[76:77], v[196:197], v[172:173], v[222:223] op_sel_hi:[1,0,1]
	v_pk_fma_f32 v[84:85], v[196:197], v[174:175], v[230:231] op_sel_hi:[1,0,1]
	v_pk_fma_f32 v[78:79], v[198:199], v[172:173], v[224:225] op_sel_hi:[1,0,1]
	v_pk_fma_f32 v[86:87], v[198:199], v[174:175], v[234:235] op_sel_hi:[1,0,1]
	ds_write_b64 v1, v[160:161] offset:55808
	s_waitcnt lgkmcnt(1)
	v_pk_mul_f32 v[164:165], v[72:73], v[4:5]
	v_pk_mul_f32 v[166:167], v[80:81], v[4:5]
	ds_read_b128 v[48:51], v2 offset:18688
	v_pk_mul_f32 v[168:169], v[72:73], v[208:209]
	v_pk_mul_f32 v[170:171], v[80:81], v[208:209]
	ds_read_b128 v[52:55], v2 offset:18704
	v_pk_fma_f32 v[164:165], v[74:75], v[6:7], v[164:165]
	v_pk_fma_f32 v[166:167], v[82:83], v[6:7], v[166:167]
	ds_read_b128 v[176:179], v2 offset:6656
	v_pk_fma_f32 v[168:169], v[74:75], v[210:211], v[168:169]
	v_pk_fma_f32 v[170:171], v[82:83], v[210:211], v[170:171]
	ds_read_b128 v[180:183], v2 offset:6672
	v_pk_fma_f32 v[164:165], v[76:77], v[8:9], v[164:165]
	v_pk_fma_f32 v[166:167], v[84:85], v[8:9], v[166:167]
	ds_read_b128 v[200:203], v2 offset:14848
	v_pk_fma_f32 v[168:169], v[76:77], v[212:213], v[168:169]
	v_pk_fma_f32 v[170:171], v[84:85], v[212:213], v[170:171]
	ds_read_b128 v[204:207], v2 offset:14864
	v_pk_fma_f32 v[164:165], v[78:79], v[10:11], v[164:165]
	v_pk_fma_f32 v[166:167], v[86:87], v[10:11], v[166:167]
	ds_read_b64 v[216:217], v3 offset:43520
	v_pk_fma_f32 v[168:169], v[78:79], v[214:215], v[168:169]
	v_pk_fma_f32 v[170:171], v[86:87], v[214:215], v[170:171]
	ds_read_b128 v[184:187], v2 offset:2560
	v_pk_mul_f32 v[218:219], v[26:27], v[40:41] op_sel_hi:[0,1]
	v_pk_mul_f32 v[226:227], v[26:27], v[40:41] op_sel:[1,0]
	ds_read_b128 v[188:191], v2 offset:2576
	v_pk_mul_f32 v[220:221], v[26:27], v[42:43] op_sel_hi:[0,1]
	v_pk_mul_f32 v[228:229], v[26:27], v[42:43] op_sel:[1,0]
	ds_read_b128 v[192:195], v2 offset:10752
	v_pk_mul_f32 v[222:223], v[26:27], v[44:45] op_sel_hi:[0,1]
	v_pk_mul_f32 v[230:231], v[26:27], v[44:45] op_sel:[1,0]
	ds_read_b128 v[196:199], v2 offset:10768
	v_pk_mul_f32 v[224:225], v[26:27], v[46:47] op_sel_hi:[0,1]
	v_pk_mul_f32 v[234:235], v[26:27], v[46:47] op_sel:[1,0]
	v_add_f32_e32 v172, v164, v165
	v_add_f32_e32 v174, v166, v167
	v_add_f32_e32 v160, v168, v169
	v_add_f32_e32 v161, v170, v171
	v_pk_fma_f32 v[218:219], v[72:73], v[12:13], v[218:219]
	v_pk_fma_f32 v[226:227], v[80:81], v[12:13], v[226:227]
	v_pk_fma_f32 v[220:221], v[74:75], v[14:15], v[220:221]
	v_pk_fma_f32 v[228:229], v[82:83], v[14:15], v[228:229]
	v_add_f32_dpp v172, v172, v172 quad_perm:[1,0,3,2] row_mask:0xf bank_mask:0xf bound_ctrl:1
	v_add_f32_dpp v174, v174, v174 quad_perm:[1,0,3,2] row_mask:0xf bank_mask:0xf bound_ctrl:1
	v_add_f32_dpp v160, v160, v160 quad_perm:[1,0,3,2] row_mask:0xf bank_mask:0xf bound_ctrl:1
	v_add_f32_dpp v161, v161, v161 quad_perm:[1,0,3,2] row_mask:0xf bank_mask:0xf bound_ctrl:1
	v_pk_fma_f32 v[222:223], v[76:77], v[28:29], v[222:223]
	v_pk_fma_f32 v[230:231], v[84:85], v[28:29], v[230:231]
	v_pk_fma_f32 v[224:225], v[78:79], v[30:31], v[224:225]
	v_pk_fma_f32 v[234:235], v[86:87], v[30:31], v[234:235]
	v_add_f32_dpp v172, v172, v172 quad_perm:[2,3,0,1] row_mask:0xf bank_mask:0xf bound_ctrl:1
	v_add_f32_dpp v174, v174, v174 quad_perm:[2,3,0,1] row_mask:0xf bank_mask:0xf bound_ctrl:1
	v_add_f32_dpp v160, v160, v160 quad_perm:[2,3,0,1] row_mask:0xf bank_mask:0xf bound_ctrl:1
	v_add_f32_dpp v161, v161, v161 quad_perm:[2,3,0,1] row_mask:0xf bank_mask:0xf bound_ctrl:1
	v_add_f32_dpp v172, v172, v172 row_half_mirror row_mask:0xf bank_mask:0xf bound_ctrl:1
	v_add_f32_dpp v174, v174, v174 row_half_mirror row_mask:0xf bank_mask:0xf bound_ctrl:1
	v_add_f32_dpp v160, v160, v160 row_half_mirror row_mask:0xf bank_mask:0xf bound_ctrl:1
	v_add_f32_dpp v161, v161, v161 row_half_mirror row_mask:0xf bank_mask:0xf bound_ctrl:1
	v_pk_fma_f32 v[72:73], v[32:33], v[172:173], v[218:219] op_sel_hi:[1,0,1]
	v_pk_fma_f32 v[80:81], v[32:33], v[174:175], v[226:227] op_sel_hi:[1,0,1]
	v_pk_fma_f32 v[74:75], v[34:35], v[172:173], v[220:221] op_sel_hi:[1,0,1]
	v_pk_fma_f32 v[82:83], v[34:35], v[174:175], v[228:229] op_sel_hi:[1,0,1]
	v_pk_fma_f32 v[76:77], v[36:37], v[172:173], v[222:223] op_sel_hi:[1,0,1]
	v_pk_fma_f32 v[84:85], v[36:37], v[174:175], v[230:231] op_sel_hi:[1,0,1]
	v_pk_fma_f32 v[78:79], v[38:39], v[172:173], v[224:225] op_sel_hi:[1,0,1]
	v_pk_fma_f32 v[86:87], v[38:39], v[174:175], v[234:235] op_sel_hi:[1,0,1]
	ds_write_b64 v1, v[160:161] offset:56064
	s_waitcnt lgkmcnt(1)
	v_pk_mul_f32 v[164:165], v[72:73], v[176:177]
	v_pk_mul_f32 v[166:167], v[80:81], v[176:177]
	ds_read_b128 v[208:211], v2 offset:18944
	v_pk_mul_f32 v[168:169], v[72:73], v[48:49]
	v_pk_mul_f32 v[170:171], v[80:81], v[48:49]
	ds_read_b128 v[212:215], v2 offset:18960
	v_pk_fma_f32 v[164:165], v[74:75], v[178:179], v[164:165]
	v_pk_fma_f32 v[166:167], v[82:83], v[178:179], v[166:167]
	ds_read_b128 v[4:7], v2 offset:6912
	v_pk_fma_f32 v[168:169], v[74:75], v[50:51], v[168:169]
	v_pk_fma_f32 v[170:171], v[82:83], v[50:51], v[170:171]
	ds_read_b128 v[8:11], v2 offset:6928
	v_pk_fma_f32 v[164:165], v[76:77], v[180:181], v[164:165]
	v_pk_fma_f32 v[166:167], v[84:85], v[180:181], v[166:167]
	ds_read_b128 v[40:43], v2 offset:15104
	v_pk_fma_f32 v[168:169], v[76:77], v[52:53], v[168:169]
	v_pk_fma_f32 v[170:171], v[84:85], v[52:53], v[170:171]
	ds_read_b128 v[44:47], v2 offset:15120
	v_pk_fma_f32 v[164:165], v[78:79], v[182:183], v[164:165]
	v_pk_fma_f32 v[166:167], v[86:87], v[182:183], v[166:167]
	ds_read_b64 v[26:27], v3 offset:43776
	v_pk_fma_f32 v[168:169], v[78:79], v[54:55], v[168:169]
	v_pk_fma_f32 v[170:171], v[86:87], v[54:55], v[170:171]
	ds_read_b128 v[12:15], v2 offset:2816
	v_pk_mul_f32 v[218:219], v[216:217], v[200:201] op_sel_hi:[0,1]
	v_pk_mul_f32 v[226:227], v[216:217], v[200:201] op_sel:[1,0]
	ds_read_b128 v[28:31], v2 offset:2832
	v_pk_mul_f32 v[220:221], v[216:217], v[202:203] op_sel_hi:[0,1]
	v_pk_mul_f32 v[228:229], v[216:217], v[202:203] op_sel:[1,0]
	ds_read_b128 v[32:35], v2 offset:11008
	v_pk_mul_f32 v[222:223], v[216:217], v[204:205] op_sel_hi:[0,1]
	v_pk_mul_f32 v[230:231], v[216:217], v[204:205] op_sel:[1,0]
	ds_read_b128 v[36:39], v2 offset:11024
	v_pk_mul_f32 v[224:225], v[216:217], v[206:207] op_sel_hi:[0,1]
	v_pk_mul_f32 v[234:235], v[216:217], v[206:207] op_sel:[1,0]
	v_add_f32_e32 v172, v164, v165
	v_add_f32_e32 v174, v166, v167
	v_add_f32_e32 v160, v168, v169
	v_add_f32_e32 v161, v170, v171
	v_pk_fma_f32 v[218:219], v[72:73], v[184:185], v[218:219]
	v_pk_fma_f32 v[226:227], v[80:81], v[184:185], v[226:227]
	v_pk_fma_f32 v[220:221], v[74:75], v[186:187], v[220:221]
	v_pk_fma_f32 v[228:229], v[82:83], v[186:187], v[228:229]
	v_add_f32_dpp v172, v172, v172 quad_perm:[1,0,3,2] row_mask:0xf bank_mask:0xf bound_ctrl:1
	v_add_f32_dpp v174, v174, v174 quad_perm:[1,0,3,2] row_mask:0xf bank_mask:0xf bound_ctrl:1
	v_add_f32_dpp v160, v160, v160 quad_perm:[1,0,3,2] row_mask:0xf bank_mask:0xf bound_ctrl:1
	v_add_f32_dpp v161, v161, v161 quad_perm:[1,0,3,2] row_mask:0xf bank_mask:0xf bound_ctrl:1
	v_pk_fma_f32 v[222:223], v[76:77], v[188:189], v[222:223]
	v_pk_fma_f32 v[230:231], v[84:85], v[188:189], v[230:231]
	v_pk_fma_f32 v[224:225], v[78:79], v[190:191], v[224:225]
	v_pk_fma_f32 v[234:235], v[86:87], v[190:191], v[234:235]
	v_add_f32_dpp v172, v172, v172 quad_perm:[2,3,0,1] row_mask:0xf bank_mask:0xf bound_ctrl:1
	v_add_f32_dpp v174, v174, v174 quad_perm:[2,3,0,1] row_mask:0xf bank_mask:0xf bound_ctrl:1
	v_add_f32_dpp v160, v160, v160 quad_perm:[2,3,0,1] row_mask:0xf bank_mask:0xf bound_ctrl:1
	v_add_f32_dpp v161, v161, v161 quad_perm:[2,3,0,1] row_mask:0xf bank_mask:0xf bound_ctrl:1
	v_add_f32_dpp v172, v172, v172 row_half_mirror row_mask:0xf bank_mask:0xf bound_ctrl:1
	v_add_f32_dpp v174, v174, v174 row_half_mirror row_mask:0xf bank_mask:0xf bound_ctrl:1
	v_add_f32_dpp v160, v160, v160 row_half_mirror row_mask:0xf bank_mask:0xf bound_ctrl:1
	v_add_f32_dpp v161, v161, v161 row_half_mirror row_mask:0xf bank_mask:0xf bound_ctrl:1
	v_pk_fma_f32 v[72:73], v[192:193], v[172:173], v[218:219] op_sel_hi:[1,0,1]
	v_pk_fma_f32 v[80:81], v[192:193], v[174:175], v[226:227] op_sel_hi:[1,0,1]
	v_pk_fma_f32 v[74:75], v[194:195], v[172:173], v[220:221] op_sel_hi:[1,0,1]
	v_pk_fma_f32 v[82:83], v[194:195], v[174:175], v[228:229] op_sel_hi:[1,0,1]
	v_pk_fma_f32 v[76:77], v[196:197], v[172:173], v[222:223] op_sel_hi:[1,0,1]
	v_pk_fma_f32 v[84:85], v[196:197], v[174:175], v[230:231] op_sel_hi:[1,0,1]
	v_pk_fma_f32 v[78:79], v[198:199], v[172:173], v[224:225] op_sel_hi:[1,0,1]
	v_pk_fma_f32 v[86:87], v[198:199], v[174:175], v[234:235] op_sel_hi:[1,0,1]
	ds_write_b64 v1, v[160:161] offset:56320
	s_waitcnt lgkmcnt(1)
	v_pk_mul_f32 v[164:165], v[72:73], v[4:5]
	v_pk_mul_f32 v[166:167], v[80:81], v[4:5]
	ds_read_b128 v[48:51], v2 offset:19200
	v_pk_mul_f32 v[168:169], v[72:73], v[208:209]
	v_pk_mul_f32 v[170:171], v[80:81], v[208:209]
	ds_read_b128 v[52:55], v2 offset:19216
	v_pk_fma_f32 v[164:165], v[74:75], v[6:7], v[164:165]
	v_pk_fma_f32 v[166:167], v[82:83], v[6:7], v[166:167]
	ds_read_b128 v[176:179], v2 offset:7168
	v_pk_fma_f32 v[168:169], v[74:75], v[210:211], v[168:169]
	v_pk_fma_f32 v[170:171], v[82:83], v[210:211], v[170:171]
	ds_read_b128 v[180:183], v2 offset:7184
	v_pk_fma_f32 v[164:165], v[76:77], v[8:9], v[164:165]
	v_pk_fma_f32 v[166:167], v[84:85], v[8:9], v[166:167]
	ds_read_b128 v[200:203], v2 offset:15360
	v_pk_fma_f32 v[168:169], v[76:77], v[212:213], v[168:169]
	v_pk_fma_f32 v[170:171], v[84:85], v[212:213], v[170:171]
	ds_read_b128 v[204:207], v2 offset:15376
	v_pk_fma_f32 v[164:165], v[78:79], v[10:11], v[164:165]
	v_pk_fma_f32 v[166:167], v[86:87], v[10:11], v[166:167]
	ds_read_b64 v[216:217], v3 offset:44032
	v_pk_fma_f32 v[168:169], v[78:79], v[214:215], v[168:169]
	v_pk_fma_f32 v[170:171], v[86:87], v[214:215], v[170:171]
	ds_read_b128 v[184:187], v2 offset:3072
	v_pk_mul_f32 v[218:219], v[26:27], v[40:41] op_sel_hi:[0,1]
	v_pk_mul_f32 v[226:227], v[26:27], v[40:41] op_sel:[1,0]
	ds_read_b128 v[188:191], v2 offset:3088
	v_pk_mul_f32 v[220:221], v[26:27], v[42:43] op_sel_hi:[0,1]
	v_pk_mul_f32 v[228:229], v[26:27], v[42:43] op_sel:[1,0]
	ds_read_b128 v[192:195], v2 offset:11264
	v_pk_mul_f32 v[222:223], v[26:27], v[44:45] op_sel_hi:[0,1]
	v_pk_mul_f32 v[230:231], v[26:27], v[44:45] op_sel:[1,0]
	ds_read_b128 v[196:199], v2 offset:11280
	v_pk_mul_f32 v[224:225], v[26:27], v[46:47] op_sel_hi:[0,1]
	v_pk_mul_f32 v[234:235], v[26:27], v[46:47] op_sel:[1,0]
	v_add_f32_e32 v172, v164, v165
	v_add_f32_e32 v174, v166, v167
	v_add_f32_e32 v160, v168, v169
	v_add_f32_e32 v161, v170, v171
	v_pk_fma_f32 v[218:219], v[72:73], v[12:13], v[218:219]
	v_pk_fma_f32 v[226:227], v[80:81], v[12:13], v[226:227]
	v_pk_fma_f32 v[220:221], v[74:75], v[14:15], v[220:221]
	v_pk_fma_f32 v[228:229], v[82:83], v[14:15], v[228:229]
	v_add_f32_dpp v172, v172, v172 quad_perm:[1,0,3,2] row_mask:0xf bank_mask:0xf bound_ctrl:1
	v_add_f32_dpp v174, v174, v174 quad_perm:[1,0,3,2] row_mask:0xf bank_mask:0xf bound_ctrl:1
	v_add_f32_dpp v160, v160, v160 quad_perm:[1,0,3,2] row_mask:0xf bank_mask:0xf bound_ctrl:1
	v_add_f32_dpp v161, v161, v161 quad_perm:[1,0,3,2] row_mask:0xf bank_mask:0xf bound_ctrl:1
	v_pk_fma_f32 v[222:223], v[76:77], v[28:29], v[222:223]
	v_pk_fma_f32 v[230:231], v[84:85], v[28:29], v[230:231]
	v_pk_fma_f32 v[224:225], v[78:79], v[30:31], v[224:225]
	v_pk_fma_f32 v[234:235], v[86:87], v[30:31], v[234:235]
	v_add_f32_dpp v172, v172, v172 quad_perm:[2,3,0,1] row_mask:0xf bank_mask:0xf bound_ctrl:1
	v_add_f32_dpp v174, v174, v174 quad_perm:[2,3,0,1] row_mask:0xf bank_mask:0xf bound_ctrl:1
	v_add_f32_dpp v160, v160, v160 quad_perm:[2,3,0,1] row_mask:0xf bank_mask:0xf bound_ctrl:1
	v_add_f32_dpp v161, v161, v161 quad_perm:[2,3,0,1] row_mask:0xf bank_mask:0xf bound_ctrl:1
	v_add_f32_dpp v172, v172, v172 row_half_mirror row_mask:0xf bank_mask:0xf bound_ctrl:1
	v_add_f32_dpp v174, v174, v174 row_half_mirror row_mask:0xf bank_mask:0xf bound_ctrl:1
	v_add_f32_dpp v160, v160, v160 row_half_mirror row_mask:0xf bank_mask:0xf bound_ctrl:1
	v_add_f32_dpp v161, v161, v161 row_half_mirror row_mask:0xf bank_mask:0xf bound_ctrl:1
	v_pk_fma_f32 v[72:73], v[32:33], v[172:173], v[218:219] op_sel_hi:[1,0,1]
	v_pk_fma_f32 v[80:81], v[32:33], v[174:175], v[226:227] op_sel_hi:[1,0,1]
	v_pk_fma_f32 v[74:75], v[34:35], v[172:173], v[220:221] op_sel_hi:[1,0,1]
	v_pk_fma_f32 v[82:83], v[34:35], v[174:175], v[228:229] op_sel_hi:[1,0,1]
	v_pk_fma_f32 v[76:77], v[36:37], v[172:173], v[222:223] op_sel_hi:[1,0,1]
	v_pk_fma_f32 v[84:85], v[36:37], v[174:175], v[230:231] op_sel_hi:[1,0,1]
	v_pk_fma_f32 v[78:79], v[38:39], v[172:173], v[224:225] op_sel_hi:[1,0,1]
	v_pk_fma_f32 v[86:87], v[38:39], v[174:175], v[234:235] op_sel_hi:[1,0,1]
	ds_write_b64 v1, v[160:161] offset:56576
	s_waitcnt lgkmcnt(1)
	v_pk_mul_f32 v[164:165], v[72:73], v[176:177]
	v_pk_mul_f32 v[166:167], v[80:81], v[176:177]
	ds_read_b128 v[208:211], v2 offset:19456
	v_pk_mul_f32 v[168:169], v[72:73], v[48:49]
	v_pk_mul_f32 v[170:171], v[80:81], v[48:49]
	ds_read_b128 v[212:215], v2 offset:19472
	v_pk_fma_f32 v[164:165], v[74:75], v[178:179], v[164:165]
	v_pk_fma_f32 v[166:167], v[82:83], v[178:179], v[166:167]
	ds_read_b128 v[4:7], v2 offset:7424
	v_pk_fma_f32 v[168:169], v[74:75], v[50:51], v[168:169]
	v_pk_fma_f32 v[170:171], v[82:83], v[50:51], v[170:171]
	ds_read_b128 v[8:11], v2 offset:7440
	v_pk_fma_f32 v[164:165], v[76:77], v[180:181], v[164:165]
	v_pk_fma_f32 v[166:167], v[84:85], v[180:181], v[166:167]
	ds_read_b128 v[40:43], v2 offset:15616
	v_pk_fma_f32 v[168:169], v[76:77], v[52:53], v[168:169]
	v_pk_fma_f32 v[170:171], v[84:85], v[52:53], v[170:171]
	ds_read_b128 v[44:47], v2 offset:15632
	v_pk_fma_f32 v[164:165], v[78:79], v[182:183], v[164:165]
	v_pk_fma_f32 v[166:167], v[86:87], v[182:183], v[166:167]
	ds_read_b64 v[26:27], v3 offset:44288
	v_pk_fma_f32 v[168:169], v[78:79], v[54:55], v[168:169]
	v_pk_fma_f32 v[170:171], v[86:87], v[54:55], v[170:171]
	ds_read_b128 v[12:15], v2 offset:3328
	v_pk_mul_f32 v[218:219], v[216:217], v[200:201] op_sel_hi:[0,1]
	v_pk_mul_f32 v[226:227], v[216:217], v[200:201] op_sel:[1,0]
	ds_read_b128 v[28:31], v2 offset:3344
	v_pk_mul_f32 v[220:221], v[216:217], v[202:203] op_sel_hi:[0,1]
	v_pk_mul_f32 v[228:229], v[216:217], v[202:203] op_sel:[1,0]
	ds_read_b128 v[32:35], v2 offset:11520
	v_pk_mul_f32 v[222:223], v[216:217], v[204:205] op_sel_hi:[0,1]
	v_pk_mul_f32 v[230:231], v[216:217], v[204:205] op_sel:[1,0]
	ds_read_b128 v[36:39], v2 offset:11536
	v_pk_mul_f32 v[224:225], v[216:217], v[206:207] op_sel_hi:[0,1]
	v_pk_mul_f32 v[234:235], v[216:217], v[206:207] op_sel:[1,0]
	v_add_f32_e32 v172, v164, v165
	v_add_f32_e32 v174, v166, v167
	v_add_f32_e32 v160, v168, v169
	v_add_f32_e32 v161, v170, v171
	v_pk_fma_f32 v[218:219], v[72:73], v[184:185], v[218:219]
	v_pk_fma_f32 v[226:227], v[80:81], v[184:185], v[226:227]
	v_pk_fma_f32 v[220:221], v[74:75], v[186:187], v[220:221]
	v_pk_fma_f32 v[228:229], v[82:83], v[186:187], v[228:229]
	v_add_f32_dpp v172, v172, v172 quad_perm:[1,0,3,2] row_mask:0xf bank_mask:0xf bound_ctrl:1
	v_add_f32_dpp v174, v174, v174 quad_perm:[1,0,3,2] row_mask:0xf bank_mask:0xf bound_ctrl:1
	v_add_f32_dpp v160, v160, v160 quad_perm:[1,0,3,2] row_mask:0xf bank_mask:0xf bound_ctrl:1
	v_add_f32_dpp v161, v161, v161 quad_perm:[1,0,3,2] row_mask:0xf bank_mask:0xf bound_ctrl:1
	v_pk_fma_f32 v[222:223], v[76:77], v[188:189], v[222:223]
	v_pk_fma_f32 v[230:231], v[84:85], v[188:189], v[230:231]
	v_pk_fma_f32 v[224:225], v[78:79], v[190:191], v[224:225]
	v_pk_fma_f32 v[234:235], v[86:87], v[190:191], v[234:235]
	v_add_f32_dpp v172, v172, v172 quad_perm:[2,3,0,1] row_mask:0xf bank_mask:0xf bound_ctrl:1
	v_add_f32_dpp v174, v174, v174 quad_perm:[2,3,0,1] row_mask:0xf bank_mask:0xf bound_ctrl:1
	v_add_f32_dpp v160, v160, v160 quad_perm:[2,3,0,1] row_mask:0xf bank_mask:0xf bound_ctrl:1
	v_add_f32_dpp v161, v161, v161 quad_perm:[2,3,0,1] row_mask:0xf bank_mask:0xf bound_ctrl:1
	v_add_f32_dpp v172, v172, v172 row_half_mirror row_mask:0xf bank_mask:0xf bound_ctrl:1
	v_add_f32_dpp v174, v174, v174 row_half_mirror row_mask:0xf bank_mask:0xf bound_ctrl:1
	v_add_f32_dpp v160, v160, v160 row_half_mirror row_mask:0xf bank_mask:0xf bound_ctrl:1
	v_add_f32_dpp v161, v161, v161 row_half_mirror row_mask:0xf bank_mask:0xf bound_ctrl:1
	v_pk_fma_f32 v[72:73], v[192:193], v[172:173], v[218:219] op_sel_hi:[1,0,1]
	v_pk_fma_f32 v[80:81], v[192:193], v[174:175], v[226:227] op_sel_hi:[1,0,1]
	v_pk_fma_f32 v[74:75], v[194:195], v[172:173], v[220:221] op_sel_hi:[1,0,1]
	v_pk_fma_f32 v[82:83], v[194:195], v[174:175], v[228:229] op_sel_hi:[1,0,1]
	v_pk_fma_f32 v[76:77], v[196:197], v[172:173], v[222:223] op_sel_hi:[1,0,1]
	v_pk_fma_f32 v[84:85], v[196:197], v[174:175], v[230:231] op_sel_hi:[1,0,1]
	v_pk_fma_f32 v[78:79], v[198:199], v[172:173], v[224:225] op_sel_hi:[1,0,1]
	v_pk_fma_f32 v[86:87], v[198:199], v[174:175], v[234:235] op_sel_hi:[1,0,1]
	ds_write_b64 v1, v[160:161] offset:56832
	s_waitcnt lgkmcnt(1)
	v_pk_mul_f32 v[164:165], v[72:73], v[4:5]
	v_pk_mul_f32 v[166:167], v[80:81], v[4:5]
	ds_read_b128 v[48:51], v2 offset:19712
	v_pk_mul_f32 v[168:169], v[72:73], v[208:209]
	v_pk_mul_f32 v[170:171], v[80:81], v[208:209]
	ds_read_b128 v[52:55], v2 offset:19728
	v_pk_fma_f32 v[164:165], v[74:75], v[6:7], v[164:165]
	v_pk_fma_f32 v[166:167], v[82:83], v[6:7], v[166:167]
	ds_read_b128 v[176:179], v2 offset:7680
	v_pk_fma_f32 v[168:169], v[74:75], v[210:211], v[168:169]
	v_pk_fma_f32 v[170:171], v[82:83], v[210:211], v[170:171]
	ds_read_b128 v[180:183], v2 offset:7696
	v_pk_fma_f32 v[164:165], v[76:77], v[8:9], v[164:165]
	v_pk_fma_f32 v[166:167], v[84:85], v[8:9], v[166:167]
	ds_read_b128 v[200:203], v2 offset:15872
	v_pk_fma_f32 v[168:169], v[76:77], v[212:213], v[168:169]
	v_pk_fma_f32 v[170:171], v[84:85], v[212:213], v[170:171]
	ds_read_b128 v[204:207], v2 offset:15888
	v_pk_fma_f32 v[164:165], v[78:79], v[10:11], v[164:165]
	v_pk_fma_f32 v[166:167], v[86:87], v[10:11], v[166:167]
	ds_read_b64 v[216:217], v3 offset:44544
	v_pk_fma_f32 v[168:169], v[78:79], v[214:215], v[168:169]
	v_pk_fma_f32 v[170:171], v[86:87], v[214:215], v[170:171]
	ds_read_b128 v[184:187], v2 offset:3584
	v_pk_mul_f32 v[218:219], v[26:27], v[40:41] op_sel_hi:[0,1]
	v_pk_mul_f32 v[226:227], v[26:27], v[40:41] op_sel:[1,0]
	ds_read_b128 v[188:191], v2 offset:3600
	v_pk_mul_f32 v[220:221], v[26:27], v[42:43] op_sel_hi:[0,1]
	v_pk_mul_f32 v[228:229], v[26:27], v[42:43] op_sel:[1,0]
	ds_read_b128 v[192:195], v2 offset:11776
	v_pk_mul_f32 v[222:223], v[26:27], v[44:45] op_sel_hi:[0,1]
	v_pk_mul_f32 v[230:231], v[26:27], v[44:45] op_sel:[1,0]
	ds_read_b128 v[196:199], v2 offset:11792
	v_pk_mul_f32 v[224:225], v[26:27], v[46:47] op_sel_hi:[0,1]
	v_pk_mul_f32 v[234:235], v[26:27], v[46:47] op_sel:[1,0]
	v_add_f32_e32 v172, v164, v165
	v_add_f32_e32 v174, v166, v167
	v_add_f32_e32 v160, v168, v169
	v_add_f32_e32 v161, v170, v171
	v_pk_fma_f32 v[218:219], v[72:73], v[12:13], v[218:219]
	v_pk_fma_f32 v[226:227], v[80:81], v[12:13], v[226:227]
	v_pk_fma_f32 v[220:221], v[74:75], v[14:15], v[220:221]
	v_pk_fma_f32 v[228:229], v[82:83], v[14:15], v[228:229]
	v_add_f32_dpp v172, v172, v172 quad_perm:[1,0,3,2] row_mask:0xf bank_mask:0xf bound_ctrl:1
	v_add_f32_dpp v174, v174, v174 quad_perm:[1,0,3,2] row_mask:0xf bank_mask:0xf bound_ctrl:1
	v_add_f32_dpp v160, v160, v160 quad_perm:[1,0,3,2] row_mask:0xf bank_mask:0xf bound_ctrl:1
	v_add_f32_dpp v161, v161, v161 quad_perm:[1,0,3,2] row_mask:0xf bank_mask:0xf bound_ctrl:1
	v_pk_fma_f32 v[222:223], v[76:77], v[28:29], v[222:223]
	v_pk_fma_f32 v[230:231], v[84:85], v[28:29], v[230:231]
	v_pk_fma_f32 v[224:225], v[78:79], v[30:31], v[224:225]
	v_pk_fma_f32 v[234:235], v[86:87], v[30:31], v[234:235]
	v_add_f32_dpp v172, v172, v172 quad_perm:[2,3,0,1] row_mask:0xf bank_mask:0xf bound_ctrl:1
	v_add_f32_dpp v174, v174, v174 quad_perm:[2,3,0,1] row_mask:0xf bank_mask:0xf bound_ctrl:1
	v_add_f32_dpp v160, v160, v160 quad_perm:[2,3,0,1] row_mask:0xf bank_mask:0xf bound_ctrl:1
	v_add_f32_dpp v161, v161, v161 quad_perm:[2,3,0,1] row_mask:0xf bank_mask:0xf bound_ctrl:1
	v_add_f32_dpp v172, v172, v172 row_half_mirror row_mask:0xf bank_mask:0xf bound_ctrl:1
	v_add_f32_dpp v174, v174, v174 row_half_mirror row_mask:0xf bank_mask:0xf bound_ctrl:1
	v_add_f32_dpp v160, v160, v160 row_half_mirror row_mask:0xf bank_mask:0xf bound_ctrl:1
	v_add_f32_dpp v161, v161, v161 row_half_mirror row_mask:0xf bank_mask:0xf bound_ctrl:1
	v_pk_fma_f32 v[72:73], v[32:33], v[172:173], v[218:219] op_sel_hi:[1,0,1]
	v_pk_fma_f32 v[80:81], v[32:33], v[174:175], v[226:227] op_sel_hi:[1,0,1]
	v_pk_fma_f32 v[74:75], v[34:35], v[172:173], v[220:221] op_sel_hi:[1,0,1]
	v_pk_fma_f32 v[82:83], v[34:35], v[174:175], v[228:229] op_sel_hi:[1,0,1]
	v_pk_fma_f32 v[76:77], v[36:37], v[172:173], v[222:223] op_sel_hi:[1,0,1]
	v_pk_fma_f32 v[84:85], v[36:37], v[174:175], v[230:231] op_sel_hi:[1,0,1]
	v_pk_fma_f32 v[78:79], v[38:39], v[172:173], v[224:225] op_sel_hi:[1,0,1]
	v_pk_fma_f32 v[86:87], v[38:39], v[174:175], v[234:235] op_sel_hi:[1,0,1]
	ds_write_b64 v1, v[160:161] offset:57088
	s_waitcnt lgkmcnt(1)
	v_pk_mul_f32 v[164:165], v[72:73], v[176:177]
	v_pk_mul_f32 v[166:167], v[80:81], v[176:177]
	ds_read_b128 v[208:211], v2 offset:19968
	v_pk_mul_f32 v[168:169], v[72:73], v[48:49]
	v_pk_mul_f32 v[170:171], v[80:81], v[48:49]
	ds_read_b128 v[212:215], v2 offset:19984
	v_pk_fma_f32 v[164:165], v[74:75], v[178:179], v[164:165]
	v_pk_fma_f32 v[166:167], v[82:83], v[178:179], v[166:167]
	ds_read_b128 v[4:7], v2 offset:7936
	v_pk_fma_f32 v[168:169], v[74:75], v[50:51], v[168:169]
	v_pk_fma_f32 v[170:171], v[82:83], v[50:51], v[170:171]
	ds_read_b128 v[8:11], v2 offset:7952
	v_pk_fma_f32 v[164:165], v[76:77], v[180:181], v[164:165]
	v_pk_fma_f32 v[166:167], v[84:85], v[180:181], v[166:167]
	ds_read_b128 v[40:43], v2 offset:16128
	v_pk_fma_f32 v[168:169], v[76:77], v[52:53], v[168:169]
	v_pk_fma_f32 v[170:171], v[84:85], v[52:53], v[170:171]
	ds_read_b128 v[44:47], v2 offset:16144
	v_pk_fma_f32 v[164:165], v[78:79], v[182:183], v[164:165]
	v_pk_fma_f32 v[166:167], v[86:87], v[182:183], v[166:167]
	ds_read_b64 v[26:27], v3 offset:44800
	v_pk_fma_f32 v[168:169], v[78:79], v[54:55], v[168:169]
	v_pk_fma_f32 v[170:171], v[86:87], v[54:55], v[170:171]
	ds_read_b128 v[12:15], v2 offset:3840
	v_pk_mul_f32 v[218:219], v[216:217], v[200:201] op_sel_hi:[0,1]
	v_pk_mul_f32 v[226:227], v[216:217], v[200:201] op_sel:[1,0]
	ds_read_b128 v[28:31], v2 offset:3856
	v_pk_mul_f32 v[220:221], v[216:217], v[202:203] op_sel_hi:[0,1]
	v_pk_mul_f32 v[228:229], v[216:217], v[202:203] op_sel:[1,0]
	ds_read_b128 v[32:35], v2 offset:12032
	v_pk_mul_f32 v[222:223], v[216:217], v[204:205] op_sel_hi:[0,1]
	v_pk_mul_f32 v[230:231], v[216:217], v[204:205] op_sel:[1,0]
	ds_read_b128 v[36:39], v2 offset:12048
	v_pk_mul_f32 v[224:225], v[216:217], v[206:207] op_sel_hi:[0,1]
	v_pk_mul_f32 v[234:235], v[216:217], v[206:207] op_sel:[1,0]
	v_add_f32_e32 v172, v164, v165
	v_add_f32_e32 v174, v166, v167
	v_add_f32_e32 v160, v168, v169
	v_add_f32_e32 v161, v170, v171
	v_pk_fma_f32 v[218:219], v[72:73], v[184:185], v[218:219]
	v_pk_fma_f32 v[226:227], v[80:81], v[184:185], v[226:227]
	v_pk_fma_f32 v[220:221], v[74:75], v[186:187], v[220:221]
	v_pk_fma_f32 v[228:229], v[82:83], v[186:187], v[228:229]
	v_add_f32_dpp v172, v172, v172 quad_perm:[1,0,3,2] row_mask:0xf bank_mask:0xf bound_ctrl:1
	v_add_f32_dpp v174, v174, v174 quad_perm:[1,0,3,2] row_mask:0xf bank_mask:0xf bound_ctrl:1
	v_add_f32_dpp v160, v160, v160 quad_perm:[1,0,3,2] row_mask:0xf bank_mask:0xf bound_ctrl:1
	v_add_f32_dpp v161, v161, v161 quad_perm:[1,0,3,2] row_mask:0xf bank_mask:0xf bound_ctrl:1
	v_pk_fma_f32 v[222:223], v[76:77], v[188:189], v[222:223]
	v_pk_fma_f32 v[230:231], v[84:85], v[188:189], v[230:231]
	v_pk_fma_f32 v[224:225], v[78:79], v[190:191], v[224:225]
	v_pk_fma_f32 v[234:235], v[86:87], v[190:191], v[234:235]
	v_add_f32_dpp v172, v172, v172 quad_perm:[2,3,0,1] row_mask:0xf bank_mask:0xf bound_ctrl:1
	v_add_f32_dpp v174, v174, v174 quad_perm:[2,3,0,1] row_mask:0xf bank_mask:0xf bound_ctrl:1
	v_add_f32_dpp v160, v160, v160 quad_perm:[2,3,0,1] row_mask:0xf bank_mask:0xf bound_ctrl:1
	v_add_f32_dpp v161, v161, v161 quad_perm:[2,3,0,1] row_mask:0xf bank_mask:0xf bound_ctrl:1
	v_add_f32_dpp v172, v172, v172 row_half_mirror row_mask:0xf bank_mask:0xf bound_ctrl:1
	v_add_f32_dpp v174, v174, v174 row_half_mirror row_mask:0xf bank_mask:0xf bound_ctrl:1
	v_add_f32_dpp v160, v160, v160 row_half_mirror row_mask:0xf bank_mask:0xf bound_ctrl:1
	v_add_f32_dpp v161, v161, v161 row_half_mirror row_mask:0xf bank_mask:0xf bound_ctrl:1
	v_pk_fma_f32 v[72:73], v[192:193], v[172:173], v[218:219] op_sel_hi:[1,0,1]
	v_pk_fma_f32 v[80:81], v[192:193], v[174:175], v[226:227] op_sel_hi:[1,0,1]
	v_pk_fma_f32 v[74:75], v[194:195], v[172:173], v[220:221] op_sel_hi:[1,0,1]
	v_pk_fma_f32 v[82:83], v[194:195], v[174:175], v[228:229] op_sel_hi:[1,0,1]
	v_pk_fma_f32 v[76:77], v[196:197], v[172:173], v[222:223] op_sel_hi:[1,0,1]
	v_pk_fma_f32 v[84:85], v[196:197], v[174:175], v[230:231] op_sel_hi:[1,0,1]
	v_pk_fma_f32 v[78:79], v[198:199], v[172:173], v[224:225] op_sel_hi:[1,0,1]
	v_pk_fma_f32 v[86:87], v[198:199], v[174:175], v[234:235] op_sel_hi:[1,0,1]
	ds_write_b64 v1, v[160:161] offset:57344
	s_waitcnt lgkmcnt(1)
	v_pk_mul_f32 v[164:165], v[72:73], v[4:5]
	v_pk_mul_f32 v[166:167], v[80:81], v[4:5]
	ds_read_b128 v[48:51], v2 offset:20224
	v_pk_mul_f32 v[168:169], v[72:73], v[208:209]
	v_pk_mul_f32 v[170:171], v[80:81], v[208:209]
	ds_read_b128 v[52:55], v2 offset:20240
	v_pk_fma_f32 v[164:165], v[74:75], v[6:7], v[164:165]
	v_pk_fma_f32 v[166:167], v[82:83], v[6:7], v[166:167]
	v_pk_fma_f32 v[168:169], v[74:75], v[210:211], v[168:169]
	v_pk_fma_f32 v[170:171], v[82:83], v[210:211], v[170:171]
	v_pk_fma_f32 v[164:165], v[76:77], v[8:9], v[164:165]
	v_pk_fma_f32 v[166:167], v[84:85], v[8:9], v[166:167]
	v_pk_fma_f32 v[168:169], v[76:77], v[212:213], v[168:169]
	v_pk_fma_f32 v[170:171], v[84:85], v[212:213], v[170:171]
	v_pk_fma_f32 v[164:165], v[78:79], v[10:11], v[164:165]
	v_pk_fma_f32 v[166:167], v[86:87], v[10:11], v[166:167]
	v_pk_fma_f32 v[168:169], v[78:79], v[214:215], v[168:169]
	v_pk_fma_f32 v[170:171], v[86:87], v[214:215], v[170:171]
	v_pk_mul_f32 v[218:219], v[26:27], v[40:41] op_sel_hi:[0,1]
	v_pk_mul_f32 v[226:227], v[26:27], v[40:41] op_sel:[1,0]
	v_pk_mul_f32 v[220:221], v[26:27], v[42:43] op_sel_hi:[0,1]
	v_pk_mul_f32 v[228:229], v[26:27], v[42:43] op_sel:[1,0]
	v_pk_mul_f32 v[222:223], v[26:27], v[44:45] op_sel_hi:[0,1]
	v_pk_mul_f32 v[230:231], v[26:27], v[44:45] op_sel:[1,0]
	v_pk_mul_f32 v[224:225], v[26:27], v[46:47] op_sel_hi:[0,1]
	v_pk_mul_f32 v[234:235], v[26:27], v[46:47] op_sel:[1,0]
	v_add_f32_e32 v172, v164, v165
	v_add_f32_e32 v174, v166, v167
	v_add_f32_e32 v160, v168, v169
	v_add_f32_e32 v161, v170, v171
	v_pk_fma_f32 v[218:219], v[72:73], v[12:13], v[218:219]
	v_pk_fma_f32 v[226:227], v[80:81], v[12:13], v[226:227]
	v_pk_fma_f32 v[220:221], v[74:75], v[14:15], v[220:221]
	v_pk_fma_f32 v[228:229], v[82:83], v[14:15], v[228:229]
	v_add_f32_dpp v172, v172, v172 quad_perm:[1,0,3,2] row_mask:0xf bank_mask:0xf bound_ctrl:1
	v_add_f32_dpp v174, v174, v174 quad_perm:[1,0,3,2] row_mask:0xf bank_mask:0xf bound_ctrl:1
	v_add_f32_dpp v160, v160, v160 quad_perm:[1,0,3,2] row_mask:0xf bank_mask:0xf bound_ctrl:1
	v_add_f32_dpp v161, v161, v161 quad_perm:[1,0,3,2] row_mask:0xf bank_mask:0xf bound_ctrl:1
	v_pk_fma_f32 v[222:223], v[76:77], v[28:29], v[222:223]
	v_pk_fma_f32 v[230:231], v[84:85], v[28:29], v[230:231]
	v_pk_fma_f32 v[224:225], v[78:79], v[30:31], v[224:225]
	v_pk_fma_f32 v[234:235], v[86:87], v[30:31], v[234:235]
	v_add_f32_dpp v172, v172, v172 quad_perm:[2,3,0,1] row_mask:0xf bank_mask:0xf bound_ctrl:1
	v_add_f32_dpp v174, v174, v174 quad_perm:[2,3,0,1] row_mask:0xf bank_mask:0xf bound_ctrl:1
	v_add_f32_dpp v160, v160, v160 quad_perm:[2,3,0,1] row_mask:0xf bank_mask:0xf bound_ctrl:1
	v_add_f32_dpp v161, v161, v161 quad_perm:[2,3,0,1] row_mask:0xf bank_mask:0xf bound_ctrl:1
	v_add_f32_dpp v172, v172, v172 row_half_mirror row_mask:0xf bank_mask:0xf bound_ctrl:1
	v_add_f32_dpp v174, v174, v174 row_half_mirror row_mask:0xf bank_mask:0xf bound_ctrl:1
	v_add_f32_dpp v160, v160, v160 row_half_mirror row_mask:0xf bank_mask:0xf bound_ctrl:1
	v_add_f32_dpp v161, v161, v161 row_half_mirror row_mask:0xf bank_mask:0xf bound_ctrl:1
	v_pk_fma_f32 v[72:73], v[32:33], v[172:173], v[218:219] op_sel_hi:[1,0,1]
	v_pk_fma_f32 v[80:81], v[32:33], v[174:175], v[226:227] op_sel_hi:[1,0,1]
	v_pk_fma_f32 v[74:75], v[34:35], v[172:173], v[220:221] op_sel_hi:[1,0,1]
	v_pk_fma_f32 v[82:83], v[34:35], v[174:175], v[228:229] op_sel_hi:[1,0,1]
	v_pk_fma_f32 v[76:77], v[36:37], v[172:173], v[222:223] op_sel_hi:[1,0,1]
	v_pk_fma_f32 v[84:85], v[36:37], v[174:175], v[230:231] op_sel_hi:[1,0,1]
	v_pk_fma_f32 v[78:79], v[38:39], v[172:173], v[224:225] op_sel_hi:[1,0,1]
	v_pk_fma_f32 v[86:87], v[38:39], v[174:175], v[234:235] op_sel_hi:[1,0,1]
	ds_write_b64 v1, v[160:161] offset:57600
	s_waitcnt lgkmcnt(2)
	v_pk_mul_f32 v[168:169], v[72:73], v[48:49]
	v_pk_mul_f32 v[170:171], v[80:81], v[48:49]
	v_pk_fma_f32 v[168:169], v[74:75], v[50:51], v[168:169]
	v_pk_fma_f32 v[170:171], v[82:83], v[50:51], v[170:171]
	s_waitcnt lgkmcnt(1)
	v_pk_fma_f32 v[168:169], v[76:77], v[52:53], v[168:169]
	v_pk_fma_f32 v[170:171], v[84:85], v[52:53], v[170:171]
	v_pk_fma_f32 v[168:169], v[78:79], v[54:55], v[168:169]
	v_pk_fma_f32 v[170:171], v[86:87], v[54:55], v[170:171]
	v_add_f32_e32 v160, v168, v169
	v_add_f32_e32 v161, v170, v171
	s_nop 0
	v_add_f32_dpp v160, v160, v160 quad_perm:[1,0,3,2] row_mask:0xf bank_mask:0xf bound_ctrl:1
	v_add_f32_dpp v161, v161, v161 quad_perm:[1,0,3,2] row_mask:0xf bank_mask:0xf bound_ctrl:1
	s_nop 0
	v_add_f32_dpp v160, v160, v160 quad_perm:[2,3,0,1] row_mask:0xf bank_mask:0xf bound_ctrl:1
	v_add_f32_dpp v161, v161, v161 quad_perm:[2,3,0,1] row_mask:0xf bank_mask:0xf bound_ctrl:1
	s_nop 0
	v_add_f32_dpp v160, v160, v160 row_half_mirror row_mask:0xf bank_mask:0xf bound_ctrl:1
	v_add_f32_dpp v161, v161, v161 row_half_mirror row_mask:0xf bank_mask:0xf bound_ctrl:1
	ds_write_b64 v1, v[160:161] offset:57856
	s_add_i32 s3, s2, 1
	s_mov_b64 s[36:37], 0

.LBB0_398:
	s_or_b64 exec, exec, s[38:39]
	v_lshl_or_b32 v2, s8, 10, v142
	v_mov_b32_e32 v3, v0
	v_lshl_add_u64 v[2:3], v[68:69], 0, v[2:3]
	global_load_ushort v212, v[2:3], off
	global_load_ushort v213, v[2:3], off offset:1024
	global_load_ushort v214, v[2:3], off offset:2048
	global_load_ushort v215, v[2:3], off offset:3072
	v_add_u32_e32 v91, v143, v102
	ds_read_b128 v[92:95], v91 offset:12544
	ds_read_b128 v[164:167], v91 offset:13056
	ds_read_b128 v[216:219], v91 offset:13568
	ds_read_b128 v[220:223], v146 offset:12544
	ds_read_b128 v[224:227], v91 offset:14592
	ds_read_b128 v[228:231], v91 offset:15104
	ds_read_b128 v[244:247], v91 offset:15616
	ds_read_b128 v[248:251], v147 offset:12544
	v_add_u32_e32 v96, 0xf000, v138
	v_add_u32_e32 v97, 0xf400, v138
	v_add_u32_e32 v159, 0xf800, v138
	s_andn2_b64 vcc, exec, s[50:51]
	s_waitcnt lgkmcnt(7)
	v_mfma_f32_16x16x32_bf16 v[92:95], v[12:15], v[92:95], 0
	s_waitcnt lgkmcnt(6)
	v_mfma_f32_16x16x32_bf16 v[164:167], v[12:15], v[164:167], 0
	s_waitcnt lgkmcnt(5)
	v_mfma_f32_16x16x32_bf16 v[216:219], v[12:15], v[216:219], 0
	s_waitcnt lgkmcnt(4)
	v_mfma_f32_16x16x32_bf16 v[220:223], v[12:15], v[220:223], 0
	s_waitcnt lgkmcnt(3)
	v_mfma_f32_16x16x32_bf16 v[224:227], v[12:15], v[224:227], 0
	s_waitcnt lgkmcnt(2)
	v_mfma_f32_16x16x32_bf16 v[228:231], v[12:15], v[228:231], 0
	s_waitcnt lgkmcnt(1)
	v_mfma_f32_16x16x32_bf16 v[244:247], v[12:15], v[244:247], 0
	s_waitcnt lgkmcnt(0)
	v_mfma_f32_16x16x32_bf16 v[248:251], v[12:15], v[248:251], 0
	ds_write2_b32 v96, v92, v164 offset0:192 offset1:208
	ds_write2_b32 v97, v93, v165 offset0:64 offset1:80
	ds_write2_b32 v97, v94, v166 offset0:192 offset1:208
	ds_write2_b32 v159, v95, v167 offset0:64 offset1:80
	ds_write2_b32 v96, v216, v220 offset0:224 offset1:240
	ds_write2_b32 v97, v217, v221 offset0:96 offset1:112
	ds_write2_b32 v97, v218, v222 offset0:224 offset1:240
	ds_write2_b32 v159, v219, v223 offset0:96 offset1:112
	ds_write2_b32 v97, v224, v228 offset1:16
	ds_write2_b32 v97, v225, v229 offset0:128 offset1:144
	ds_write2_b32 v159, v226, v230 offset1:16
	ds_write2_b32 v159, v227, v231 offset0:128 offset1:144
	ds_write2_b32 v97, v244, v248 offset0:32 offset1:48
	ds_write2_b32 v97, v245, v249 offset0:160 offset1:176
	ds_write2_b32 v159, v246, v250 offset0:32 offset1:48
	ds_write2_b32 v159, v247, v251 offset0:160 offset1:176
	s_waitcnt lgkmcnt(0)
	ds_read2st64_b32 v[12:13], v139 offset0:243 offset1:244
	v_pk_mul_f32 v[14:15], v[56:57], v[60:61]
	s_nop 0
	v_sub_f32_e32 v14, v14, v15
	s_waitcnt lgkmcnt(0)
	v_add_f32_e32 v12, v14, v12
	v_pk_mul_f32 v[14:15], v[56:57], v[60:61] op_sel:[0,1] op_sel_hi:[1,0]
	ds_read2st64_b32 v[60:61], v139 offset0:245 offset1:246
	v_add_f32_e32 v14, v14, v15
	v_add_f32_e32 v14, v14, v13
	v_cvt_pk_bf16_f32 v13, v12, v0
	ds_write_b16 v141, v13 offset:8192
	v_cvt_pk_bf16_f32 v13, v14, v0
	v_pk_mul_f32 v[14:15], v[64:65], v[14:15] op_sel_hi:[1,0]
	ds_write_b16 v141, v13 offset:8320
	v_pk_fma_f32 v[92:93], v[56:57], v[12:13], v[14:15] neg_lo:[0,0,1] neg_hi:[0,0,1]
	v_pk_fma_f32 v[12:13], v[56:57], v[12:13], v[14:15] op_sel_hi:[1,0,1]
	s_nop 0
	v_mov_b32_e32 v93, v13
	s_waitcnt lgkmcnt(2)
	v_pk_add_f32 v[12:13], v[92:93], v[60:61]
	s_nop 0
	v_cvt_pk_bf16_f32 v14, v12, v0
	ds_write_b16 v141, v14 offset:8464
	v_cvt_pk_bf16_f32 v14, v13, v0
	ds_write_b16 v141, v14 offset:8592
	ds_read2st64_b32 v[14:15], v139 offset0:247 offset1:248
	v_pk_mul_f32 v[60:61], v[56:57], v[12:13]
	v_pk_mul_f32 v[12:13], v[64:65], v[12:13]
	v_sub_f32_e32 v60, v60, v61
	v_add_f32_e32 v12, v12, v13
	s_waitcnt lgkmcnt(0)
	v_add_f32_e32 v14, v60, v14
	v_cvt_pk_bf16_f32 v13, v14, v0
	ds_read2st64_b32 v[60:61], v139 offset0:249 offset1:250
	v_add_f32_e32 v12, v12, v15
	ds_write_b16 v141, v13 offset:8736
	v_cvt_pk_bf16_f32 v13, v12, v0
	ds_write_b16 v141, v13 offset:8864
	v_pk_mul_f32 v[12:13], v[64:65], v[12:13] op_sel_hi:[1,0]
	s_nop 0
	v_pk_fma_f32 v[92:93], v[56:57], v[14:15], v[12:13] neg_lo:[0,0,1] neg_hi:[0,0,1]
	v_pk_fma_f32 v[12:13], v[56:57], v[14:15], v[12:13] op_sel_hi:[1,0,1]
	s_nop 0
	v_mov_b32_e32 v93, v13
	s_waitcnt lgkmcnt(2)
	v_pk_add_f32 v[12:13], v[92:93], v[60:61]
	s_nop 0
	v_cvt_pk_bf16_f32 v14, v12, v0
	ds_write_b16 v141, v14 offset:9008
	v_cvt_pk_bf16_f32 v14, v13, v0
	ds_write_b16 v141, v14 offset:9136
	ds_read2st64_b32 v[14:15], v139 offset0:251 offset1:252
	v_pk_mul_f32 v[60:61], v[56:57], v[12:13]
	v_pk_mul_f32 v[12:13], v[64:65], v[12:13]
	v_sub_f32_e32 v60, v60, v61
	v_add_f32_e32 v12, v12, v13
	s_waitcnt lgkmcnt(0)
	v_add_f32_e32 v14, v60, v14
	v_cvt_pk_bf16_f32 v13, v14, v0
	ds_read2st64_b32 v[60:61], v139 offset0:253 offset1:254
	v_add_f32_e32 v12, v12, v15
	ds_write_b16 v141, v13 offset:9280
	v_cvt_pk_bf16_f32 v13, v12, v0
	ds_write_b16 v141, v13 offset:9408
	v_pk_mul_f32 v[12:13], v[64:65], v[12:13] op_sel_hi:[1,0]
	s_nop 0
	v_pk_fma_f32 v[92:93], v[56:57], v[14:15], v[12:13] neg_lo:[0,0,1] neg_hi:[0,0,1]
	v_pk_fma_f32 v[12:13], v[56:57], v[14:15], v[12:13] op_sel_hi:[1,0,1]
	s_nop 0
	v_mov_b32_e32 v93, v13
	s_waitcnt lgkmcnt(2)
	v_pk_add_f32 v[12:13], v[92:93], v[60:61]
	s_nop 0
	v_cvt_pk_bf16_f32 v14, v12, v0
	ds_write_b16 v141, v14 offset:9552
	v_cvt_pk_bf16_f32 v14, v13, v0
	ds_write_b16 v141, v14 offset:9680
	ds_read_b32 v91, v139 offset:65280
	ds_read2st64_b32 v[14:15], v140 offset0:13 offset1:14
	v_pk_mul_f32 v[60:61], v[56:57], v[12:13]
	v_pk_mul_f32 v[12:13], v[64:65], v[12:13]
	v_sub_f32_e32 v60, v60, v61
	ds_read2st64_b32 v[92:93], v140 offset0:15 offset1:16
	s_waitcnt lgkmcnt(2)
	v_add_f32_e32 v60, v60, v91
	v_add_f32_e32 v12, v12, v13
	v_cvt_pk_bf16_f32 v13, v60, v0
	s_waitcnt lgkmcnt(1)
	v_add_f32_e32 v12, v12, v14
	ds_write_b16 v141, v13 offset:9824
	v_cvt_pk_bf16_f32 v13, v12, v0
	ds_write_b16 v141, v13 offset:9952
	v_pk_mul_f32 v[12:13], v[64:65], v[12:13] op_sel_hi:[1,0]
	s_nop 0
	v_pk_fma_f32 v[94:95], v[56:57], v[60:61], v[12:13] neg_lo:[0,0,1] neg_hi:[0,0,1]
	v_pk_fma_f32 v[12:13], v[56:57], v[60:61], v[12:13] op_sel_hi:[1,0,1]
	s_nop 0
	v_mov_b32_e32 v95, v13
	v_mov_b32_e32 v12, v15
	s_waitcnt lgkmcnt(2)
	v_mov_b32_e32 v13, v92
	v_pk_add_f32 v[12:13], v[94:95], v[12:13]
	s_nop 0
	v_cvt_pk_bf16_f32 v14, v12, v0
	ds_write_b16 v141, v14 offset:10096
	v_cvt_pk_bf16_f32 v14, v13, v0
	ds_write_b16 v141, v14 offset:10224
	ds_read2st64_b32 v[14:15], v140 offset0:17 offset1:18
	v_pk_mul_f32 v[60:61], v[56:57], v[12:13]
	v_pk_mul_f32 v[12:13], v[64:65], v[12:13]
	v_sub_f32_e32 v60, v60, v61
	v_add_f32_e32 v60, v60, v93
	ds_read2st64_b32 v[92:93], v140 offset0:19 offset1:20
	v_add_f32_e32 v12, v12, v13
	v_cvt_pk_bf16_f32 v13, v60, v0
	s_waitcnt lgkmcnt(1)
	v_add_f32_e32 v12, v12, v14
	ds_write_b16 v141, v13 offset:10368
	v_cvt_pk_bf16_f32 v13, v12, v0
	ds_write_b16 v141, v13 offset:10496
	v_pk_mul_f32 v[12:13], v[64:65], v[12:13] op_sel_hi:[1,0]
	s_nop 0
	v_pk_fma_f32 v[94:95], v[56:57], v[60:61], v[12:13] neg_lo:[0,0,1] neg_hi:[0,0,1]
	v_pk_fma_f32 v[12:13], v[56:57], v[60:61], v[12:13] op_sel_hi:[1,0,1]
	s_nop 0
	v_mov_b32_e32 v95, v13
	v_mov_b32_e32 v12, v15
	s_waitcnt lgkmcnt(2)
	v_mov_b32_e32 v13, v92
	v_pk_add_f32 v[12:13], v[94:95], v[12:13]
	s_nop 0
	v_cvt_pk_bf16_f32 v14, v12, v0
	ds_write_b16 v141, v14 offset:10640
	v_cvt_pk_bf16_f32 v14, v13, v0
	ds_write_b16 v141, v14 offset:10768
	ds_read2st64_b32 v[14:15], v140 offset0:21 offset1:22
	v_pk_mul_f32 v[60:61], v[56:57], v[12:13]
	v_pk_mul_f32 v[12:13], v[64:65], v[12:13]
	v_sub_f32_e32 v60, v60, v61
	v_add_f32_e32 v60, v60, v93
	ds_read2st64_b32 v[92:93], v140 offset0:23 offset1:24
	v_add_f32_e32 v12, v12, v13
	v_cvt_pk_bf16_f32 v13, v60, v0
	s_waitcnt lgkmcnt(1)
	v_add_f32_e32 v12, v12, v14
	ds_write_b16 v141, v13 offset:10912
	v_cvt_pk_bf16_f32 v13, v12, v0
	ds_write_b16 v141, v13 offset:11040
	v_pk_mul_f32 v[12:13], v[64:65], v[12:13] op_sel_hi:[1,0]
	s_nop 0
	v_pk_fma_f32 v[94:95], v[56:57], v[60:61], v[12:13] neg_lo:[0,0,1] neg_hi:[0,0,1]
	v_pk_fma_f32 v[12:13], v[56:57], v[60:61], v[12:13] op_sel_hi:[1,0,1]
	s_nop 0
	v_mov_b32_e32 v95, v13
	v_mov_b32_e32 v12, v15
	s_waitcnt lgkmcnt(2)
	v_mov_b32_e32 v13, v92
	v_pk_add_f32 v[12:13], v[94:95], v[12:13]
	s_nop 0
	v_cvt_pk_bf16_f32 v14, v12, v0
	ds_write_b16 v141, v14 offset:11184
	v_cvt_pk_bf16_f32 v14, v13, v0
	ds_write_b16 v141, v14 offset:11312
	ds_read2st64_b32 v[14:15], v140 offset0:25 offset1:26
	v_pk_mul_f32 v[60:61], v[56:57], v[12:13]
	v_pk_mul_f32 v[12:13], v[64:65], v[12:13]
	v_sub_f32_e32 v60, v60, v61
	v_add_f32_e32 v60, v60, v93
	ds_read2st64_b32 v[92:93], v140 offset0:27 offset1:28
	v_add_f32_e32 v12, v12, v13
	v_cvt_pk_bf16_f32 v13, v60, v0
	s_waitcnt lgkmcnt(1)
	v_add_f32_e32 v12, v12, v14
	ds_write_b16 v141, v13 offset:11456
	v_cvt_pk_bf16_f32 v13, v12, v0
	ds_write_b16 v141, v13 offset:11584
	v_pk_mul_f32 v[12:13], v[64:65], v[12:13] op_sel_hi:[1,0]
	s_nop 0
	v_pk_fma_f32 v[94:95], v[56:57], v[60:61], v[12:13] neg_lo:[0,0,1] neg_hi:[0,0,1]
	v_pk_fma_f32 v[12:13], v[56:57], v[60:61], v[12:13] op_sel_hi:[1,0,1]
	s_nop 0
	v_mov_b32_e32 v95, v13
	v_mov_b32_e32 v12, v15
	s_waitcnt lgkmcnt(2)
	v_mov_b32_e32 v13, v92
	v_pk_add_f32 v[12:13], v[94:95], v[12:13]
	s_nop 0
	v_cvt_pk_bf16_f32 v14, v12, v0
	ds_write_b16 v141, v14 offset:11728
	v_cvt_pk_bf16_f32 v14, v13, v0
	ds_write_b16 v141, v14 offset:11856
	ds_read2st64_b32 v[14:15], v140 offset0:29 offset1:30
	v_pk_mul_f32 v[60:61], v[56:57], v[12:13]
	v_pk_mul_f32 v[12:13], v[64:65], v[12:13]
	v_sub_f32_e32 v60, v60, v61
	v_add_f32_e32 v60, v60, v93
	v_add_f32_e32 v12, v12, v13
	v_cvt_pk_bf16_f32 v13, v60, v0
	s_waitcnt lgkmcnt(0)
	v_add_f32_e32 v12, v12, v14
	ds_write_b16 v141, v13 offset:12000
	v_cvt_pk_bf16_f32 v13, v12, v0
	ds_write_b16 v141, v13 offset:12128
	ds_read_b32 v13, v140 offset:7936
	s_waitcnt lgkmcnt(0)
	v_pk_mul_f32 v[92:93], v[64:65], v[12:13] op_sel_hi:[1,0]
	s_nop 0
	v_pk_fma_f32 v[94:95], v[56:57], v[60:61], v[92:93] neg_lo:[0,0,1] neg_hi:[0,0,1]
	v_pk_fma_f32 v[60:61], v[56:57], v[60:61], v[92:93] op_sel_hi:[1,0,1]
	v_mov_b32_e32 v12, v15
	v_mov_b32_e32 v95, v61
	v_pk_add_f32 v[60:61], v[94:95], v[12:13]
	s_nop 0
	v_cvt_pk_bf16_f32 v12, v60, v0
	ds_write_b16 v141, v12 offset:12272
	v_cvt_pk_bf16_f32 v12, v61, v0
	ds_write_b16 v141, v12 offset:12400
	s_waitcnt lgkmcnt(0)
	ds_read_b128 v[12:15], v144 offset:8192
	ds_read_b128 v[92:95], v145 offset:16640
	ds_read_b128 v[216:219], v144 offset:8256
	ds_read_b128 v[220:223], v145 offset:16704
	ds_read_b128 v[224:227], v144 offset:8320
	ds_read_b128 v[228:231], v145 offset:16768
	ds_read_b128 v[244:247], v144 offset:8384
	ds_read_b128 v[248:251], v145 offset:16832
	s_waitcnt lgkmcnt(6)
	v_mfma_f32_16x16x32_bf16 v[12:15], v[12:15], v[92:95], 0
	s_waitcnt lgkmcnt(4)
	v_mfma_f32_16x16x32_bf16 v[12:15], v[216:219], v[220:223], v[12:15]
	s_waitcnt lgkmcnt(2)
	v_mfma_f32_16x16x32_bf16 v[12:15], v[224:227], v[228:231], v[12:15]
	s_waitcnt lgkmcnt(0)
	v_mfma_f32_16x16x32_bf16 v[12:15], v[244:247], v[248:251], v[12:15]
	s_nop 7
	s_waitcnt vmcnt(0)
	v_lshlrev_b32_e32 v90, 16, v212
	v_lshlrev_b32_e32 v89, 16, v213
	v_lshlrev_b32_e32 v88, 16, v214
	v_lshlrev_b32_e32 v1, 16, v215
	v_fma_f32 v12, v148, v90, v12
	v_mul_f32_e32 v90, 0x3d372713, v12
	v_mul_f32_e32 v90, v12, v90
	v_fma_f32 v90, v12, v90, v12
	v_mul_f32_e32 v90, 0x3f4c422a, v90
	v_add_f32_e32 v90, v90, v90
	v_mul_f32_e32 v90, 0x3fb8aa3b, v90
	v_exp_f32_e32 v90, v90
	v_mul_f32_e32 v12, 0.5, v12
	v_fmac_f32_e32 v15, v148, v1
	v_mul_f32_e32 v1, 0x3d372713, v15
	v_add_f32_e32 v90, 1.0, v90
	v_rcp_f32_e32 v90, v90
	v_mul_f32_e32 v1, v15, v1
	v_fma_f32 v1, v15, v1, v15
	v_mul_f32_e32 v1, 0x3f4c422a, v1
	v_fma_f32 v90, v90, -2.0, 1.0
	v_add_f32_e32 v90, 1.0, v90
	v_mul_f32_e32 v12, v12, v90
	v_cvt_pk_bf16_f32 v12, v12, v0
	global_store_short v[2:3], v12, off
	v_fma_f32 v12, v148, v89, v13
	v_mul_f32_e32 v13, 0x3d372713, v12
	v_mul_f32_e32 v13, v12, v13
	v_fma_f32 v13, v12, v13, v12
	v_mul_f32_e32 v13, 0x3f4c422a, v13
	v_add_f32_e32 v13, v13, v13
	v_mul_f32_e32 v13, 0x3fb8aa3b, v13
	v_exp_f32_e32 v13, v13
	v_mul_f32_e32 v12, 0.5, v12
	v_add_f32_e32 v1, v1, v1
	v_mul_f32_e32 v1, 0x3fb8aa3b, v1
	v_add_f32_e32 v13, 1.0, v13
	v_rcp_f32_e32 v13, v13
	v_exp_f32_e32 v1, v1
	v_fma_f32 v13, v13, -2.0, 1.0
	v_add_f32_e32 v13, 1.0, v13
	v_mul_f32_e32 v12, v12, v13
	v_cvt_pk_bf16_f32 v12, v12, v0
	global_store_short v[2:3], v12, off offset:1024
	v_fma_f32 v12, v148, v88, v14
	v_mul_f32_e32 v13, 0x3d372713, v12
	v_mul_f32_e32 v13, v12, v13
	v_fma_f32 v13, v12, v13, v12
	v_mul_f32_e32 v13, 0x3f4c422a, v13
	v_add_f32_e32 v13, v13, v13
	v_mul_f32_e32 v13, 0x3fb8aa3b, v13
	v_exp_f32_e32 v13, v13
	v_add_f32_e32 v1, 1.0, v1
	v_rcp_f32_e32 v1, v1
	v_mul_f32_e32 v12, 0.5, v12
	v_add_f32_e32 v13, 1.0, v13
	v_rcp_f32_e32 v13, v13
	v_fma_f32 v1, v1, -2.0, 1.0
	v_add_f32_e32 v1, 1.0, v1
	v_fma_f32 v13, v13, -2.0, 1.0
	v_add_f32_e32 v13, 1.0, v13
	v_mul_f32_e32 v12, v12, v13
	v_cvt_pk_bf16_f32 v12, v12, v0
	global_store_short v[2:3], v12, off offset:2048
	v_mul_f32_e32 v12, 0.5, v15
	v_mul_f32_e32 v1, v12, v1
	v_cvt_pk_bf16_f32 v1, v1, v0
	global_store_short v[2:3], v1, off offset:3072
	s_waitcnt lgkmcnt(0)
	v_lshlrev_b32_e32 v1, 2, v128
	s_cbranch_vccnz .LBB0_408
	s_waitcnt vmcnt(4)
	v_lshlrev_b32_e32 v16, 16, v176
	v_lshlrev_b32_e32 v30, 16, v177
	v_lshlrev_b32_e32 v32, 16, v178
	v_lshlrev_b32_e32 v36, 16, v179
	v_lshlrev_b32_e32 v17, 16, v180
	v_lshlrev_b32_e32 v26, 16, v181
	v_lshlrev_b32_e32 v27, 16, v182
	v_lshlrev_b32_e32 v28, 16, v183
	v_lshlrev_b32_e32 v29, 16, v184
	v_lshlrev_b32_e32 v31, 16, v185
	v_lshlrev_b32_e32 v33, 16, v186
	v_lshlrev_b32_e32 v37, 16, v187
	v_lshlrev_b32_e32 v34, 16, v188
	v_lshlrev_b32_e32 v35, 16, v189
	v_lshlrev_b32_e32 v38, 16, v190
	v_lshlrev_b32_e32 v39, 16, v195
	v_lshlrev_b32_e32 v40, 16, v197
	v_lshlrev_b32_e32 v43, 16, v198
	v_lshlrev_b32_e32 v42, 16, v199
	v_lshlrev_b32_e32 v45, 16, v200
	v_lshlrev_b32_e32 v44, 16, v201
	v_lshlrev_b32_e32 v46, 16, v203
	v_lshlrev_b32_e32 v49, 16, v204
	v_lshlrev_b32_e32 v48, 16, v205
	v_lshlrev_b32_e32 v41, 16, v196
	v_lshlrev_b32_e32 v47, 16, v202
	v_lshlrev_b32_e32 v51, 16, v206
	v_lshlrev_b32_e32 v50, 16, v207
	v_lshlrev_b32_e32 v53, 16, v191
	v_lshlrev_b32_e32 v52, 16, v193
	v_lshlrev_b32_e32 v55, 16, v192
	v_lshlrev_b32_e32 v54, 16, v194
	v_add_f32_e32 v88, v155, v35
	v_mul_f32_e32 v88, 0xbfb8aa3b, v88
	v_exp_f32_e32 v88, v88
	v_pk_add_f32 v[12:13], v[32:33], v[26:27] neg_lo:[0,1] neg_hi:[0,1]
	v_pk_add_f32 v[2:3], v[30:31], v[16:17] neg_lo:[0,1] neg_hi:[0,1]
	v_fma_f32 v13, v150, v13, v27
	v_add_f32_e32 v88, 1.0, v88
	v_rcp_f32_e32 v88, v88
	v_mul_f32_e32 v92, v157, v13
	v_fma_f32 v3, v149, v3, v17
	s_bitcmp1_b32 s3, 0
	v_mul_f32_e32 v89, 0xbf6002b1, v88
	v_cmp_gt_f32_e32 vcc, s85, v89
	s_cselect_b32 s8, 0x5000, 0
	v_mov_b32_e32 v94, v0
	v_cndmask_b32_e32 v89, 0, v239, vcc
	v_fmac_f32_e32 v89, 0xbf6002b1, v88
	v_exp_f32_e32 v88, v89
	v_cndmask_b32_e32 v89, 0, v236, vcc
	s_add_i32 s9, s8, 0
	s_mul_i32 s8, s3, 0xab
	v_ldexp_f32 v90, v88, v89
	v_add_f32_e32 v88, v154, v39
	v_mul_f32_e32 v88, 0xbfb8aa3b, v88
	v_exp_f32_e32 v88, v88
	v_mov_b32_e32 v89, v0
	s_bfe_u32 s8, s8, 0x70009
	s_mul_i32 s8, s8, 3
	v_add_f32_e32 v88, 1.0, v88
	v_rcp_f32_e32 v91, v88
	v_mul_f32_e32 v88, v92, v92
	s_sub_i32 s8, s3, s8
	s_and_b32 s8, s8, 0xff
	v_mov_b32_dpp v89, v88 quad_perm:[1,0,3,2] row_mask:0xf bank_mask:0xf
	v_fmac_f32_e32 v89, v92, v92
	s_mulk_i32 s8, 0x1100
	s_add_i32 s8, s8, 0
	v_add_f32_dpp v88, v89, v89 quad_perm:[2,3,0,1] row_mask:0xf bank_mask:0xf bound_ctrl:1
	v_pk_add_f32 v[14:15], v[36:37], v[28:29] neg_lo:[0,1] neg_hi:[0,1]
	s_nop 0
	v_add_f32_dpp v88, v88, v88 row_half_mirror row_mask:0xf bank_mask:0xf bound_ctrl:1
	v_fma_f32 v15, v151, v15, v29
	s_nop 0
	v_add_f32_dpp v88, v88, v88 row_mirror row_mask:0xf bank_mask:0xf bound_ctrl:1
	s_nop 0
	v_readlane_b32 s26, v88, 16
	v_readlane_b32 s27, v88, 48
	v_readlane_b32 s24, v88, 0
	v_readlane_b32 s25, v88, 32
	v_mov_b32_e32 v88, s26
	v_mov_b32_e32 v89, s27
	v_pk_add_f32 v[88:89], s[24:25], v[88:89]
	s_nop 0
	v_add_f32_e32 v88, v88, v89
	v_add_f32_e32 v88, 0x2b8cbccc, v88
	v_cmp_gt_f32_e32 vcc, s82, v88
	v_mul_f32_e32 v89, 0x4b800000, v88
	s_nop 0
	v_cndmask_b32_e32 v88, v88, v89, vcc
	v_rsq_f32_e32 v88, v88
	s_nop 0
	v_mul_f32_e32 v89, 0x45800000, v88
	v_cndmask_b32_e32 v88, v88, v89, vcc
	v_add_f32_e32 v89, -1.0, v91
	v_fma_f32 v89, v158, v89, 1.0
	v_mul_f32_e32 v13, v89, v13
	v_mul_f32_e32 v89, v13, v3
	v_mul_f32_e32 v93, v156, v89
	v_mul_f32_e64 v88, v92, -v88
	s_nop 0
	v_mov_b32_dpp v94, v93 quad_perm:[1,0,3,2] row_mask:0xf bank_mask:0xf
	v_fmac_f32_e32 v94, v156, v89
	s_nop 1
	v_add_f32_dpp v89, v94, v94 quad_perm:[2,3,0,1] row_mask:0xf bank_mask:0xf bound_ctrl:1
	s_nop 1
	v_add_f32_dpp v89, v89, v89 row_half_mirror row_mask:0xf bank_mask:0xf bound_ctrl:1
	s_nop 1
	v_add_f32_dpp v89, v89, v89 row_mirror row_mask:0xf bank_mask:0xf bound_ctrl:1
	s_nop 0
	v_readlane_b32 s38, v89, 0
	v_readlane_b32 s52, v89, 16
	v_readlane_b32 s39, v89, 32
	v_readlane_b32 s53, v89, 48
	v_add_u32_e32 v89, s9, v1
	ds_write2st64_b32 v89, v90, v88 offset1:16
	v_mul_f32_e64 v88, v91, -v88
	ds_write2st64_b32 v89, v88, v13 offset0:32 offset1:48
	ds_write_b32 v89, v3 offset:16384
	v_add_u32_e32 v3, s8, v1
	ds_write_b32 v3, v15 offset:40960
	s_and_saveexec_b64 s[50:51], s[44:45]
	s_cbranch_execz .LBB0_401
	s_lshl_b32 s24, s96, 2
	v_mov_b32_e32 v88, s52
	v_mov_b32_e32 v89, s53
	s_add_i32 s24, s8, s24
	v_pk_add_f32 v[88:89], s[38:39], v[88:89]
	v_mov_b32_e32 v13, s24
	v_add_f32_e32 v3, v88, v89
	ds_write_b32 v13, v3 offset:45056
